# V staged in P-native key order: 8 permlane32_swap per tile removed in A,B,C loops; B loop stagger+SGPR DMA
# speedup vs baseline: 1.0109x; 1.0109x over previous
; DI float bf2f(unsigned short b) { return __uint_as_float(((unsigned)b) << 16); }
; template <int DQK, int MODE>
; DI void attn_body(const AttnArgs& a, char* lds) {
;     ...
;     const bf16_t* Qw = a.Q + (size_t)(wid * 32 + r32) * a.ldq + hi * 8;
; #pragma unroll
;     for (int d0 = 0; d0 < NQR; ++d0) qr[d0] = *(const bf16x8*)(Qw + d0 * 16);
;     if constexpr (MODE == 2) {
;         const f32x2* rp = a.rope + (size_t)(a.qpos0 + wid * 32 + r32) * 32 + hi * 8;
; #pragma unroll
;         for (int dd = 0; dd < 2; ++dd) {
;             bf16x8 x1 = *(const bf16x8*)(Qw + (8 + dd) * 16), x2 = *(const bf16x8*)(Qw + (10 + dd) * 16); bf16x8 y1, y2;
; #pragma unroll
;             for (int j = 0; j < 8; ++j) { const f32x2 cs = rp[dd * 16 + j]; const float a1 = bf2f((unsigned short)x1[j]), a2 = bf2f((unsigned short)x2[j]);
;                 y1[j] = (short)f2bf(a1 * cs.x - a2 * cs.y); y2[j] = (short)f2bf(a1 * cs.y + a2 * cs.x); }
;             *(bf16x8*)(qrl + (8 + dd - NQR) * 1024) = y1; *(bf16x8*)(qrl + (10 + dd - NQR) * 1024) = y2; }
; #pragma unroll
;         for (int d0 = NQR; d0 < 8; ++d0) *(bf16x8*)(qrl + (d0 - NQR) * 1024) = *(const bf16x8*)(Qw + d0 * 16);
;     }
;     const int sr = tid >> 4, sc = (tid & 15) * 8, vst0 = v_st(sr, sc), vst1 = v_st(32 + sr, sc);
;     const bf16_t* vp0 = a.V + (size_t)sr * a.ldv + sc; const bf16_t* vp1 = a.V + (size_t)(32 + sr) * a.ldv + sc;
;     const bf16_t* kp[KCH]; int kld[KCH], kdst[KCH];
; #pragma unroll
;     for (int i = 0; i < KCH; ++i) { const int e = tid + i * NTHR, row = e / CPR, c = e % CPR;
;         if (MODE == 2 && c >= 16) { kp[i] = a.K2 + (size_t)row * a.ldk2 + (c - 16) * 8; kld[i] = a.ldk2; }
;         else { kp[i] = a.K + (size_t)row * a.ldk + c * 8; kld[i] = a.ldk; }
;         kdst[i] = row * KROWB + ((c * 16) ^ ksw(row)); }
;     const int vb0 = (int)(uintptr_t)V_lds + v_rd_base(lane);
;     struct { bf16x8 vs0, vs1, ks[KCH]; } st_[SD];
;     ...
;     constexpr int NI = 2 + KCH;
;     const bf16_t* sp[NI]; int sld[NI];
; #pragma unroll
;     for (int i = 0; i < NI; ++i) { const int b = wid + 8 * i;
;         if (i < 2) { const int pos = b * 1024 + lane * 16, stl = pos >> 9, q = (pos & 511) >> 1, kk = (stl >> 2) * 8 + (q >> 5), c = (stl & 3) * 32 + (q & 31);
;             const int k = (kk & ~0xC) | ((kk & 4) << 1) | ((kk & 8) >> 1);
;             sp[i] = a.V + (size_t)k * a.ldv + c; sld[i] = a.ldv;
.LBB0_737:
	s_lshl_b64 s[16:17], s[68:69], 1
	v_mov_b32_e32 v161, v146
	s_add_u32 s36, s28, s16
	s_addc_u32 s37, s29, s17
	v_ashrrev_i32_e32 v164, 6, v161
	v_and_b32_e32 v165, 31, v161
	v_lshlrev_b32_e32 v163, 5, v164
	v_bfe_u32 v166, v161, 5, 1
	v_or_b32_e32 v0, v163, v165
	s_waitcnt lgkmcnt(0)
	v_mov_b64_e32 v[2:3], s[36:37]
	v_and_b32_e32 v162, 63, v161
	v_mad_i64_i32 v[2:3], s[36:37], v0, s92, v[2:3]
	v_lshlrev_b32_e32 v0, 4, v166
	v_lshl_add_u64 v[2:3], v[2:3], 0, v[0:1]
	v_lshlrev_b32_e32 v4, 3, v162
	s_waitcnt lgkmcnt(0)
	s_barrier
	global_load_dwordx4 v[130:133], v[2:3], off
	global_load_dwordx4 v[134:137], v[2:3], off offset:32
	global_load_dwordx4 v[138:141], v[2:3], off offset:64
	global_load_dwordx4 v[142:145], v[2:3], off offset:96
	v_and_b32_e32 v2, 24, v4
	v_bfe_u32 v5, v161, 2, 2
	v_lshrrev_b32_e32 v7, 1, v161
	v_lshlrev_b32_e32 v8, 2, v164
	v_lshlrev_b32_e32 v9, 2, v164
	v_and_or_b32 v6, v161, s13, v2
	v_bfe_u32 v5, v161, 2, 3
	v_and_b32_e32 v8, -16, v8
	v_and_b32_e32 v9, 8, v9
	v_lshlrev_b32_e32 v6, 1, v6
	v_mov_b32_e32 v7, v1
	v_or3_b32 v10, v5, v9, v8
	v_or3_b32 v5, v8, v9, v5
	v_lshl_add_u64 v[6:7], s[62:63], 0, v[6:7]
	v_add_u32_e32 v5, 32, v5
	v_lshlrev_b32_e32 v3, 4, v162
	v_mad_i64_i32 v[150:151], s[36:37], v10, s92, v[6:7]
	v_mad_i64_i32 v[152:153], s[36:37], v5, s92, v[6:7]
	v_lshlrev_b32_e32 v5, 10, v164
	v_bfe_i32 v6, v164, 21, 1
	v_or_b32_e32 v5, v5, v3
	v_lshrrev_b32_e32 v6, 25, v6
	v_add_u32_e32 v6, v5, v6
	s_add_u32 s16, s24, s16
	v_ashrrev_i32_e32 v8, 7, v6
	v_and_b32_e32 v6, 0xffffff80, v6
	s_addc_u32 s17, s25, s17
	v_sub_u32_e32 v5, v5, v6
	v_lshlrev_b32_e32 v6, 3, v8
	v_bitop3_b32 v5, v5, v6, s34 bitop3:0x78
	v_mov_b64_e32 v[6:7], s[16:17]
	v_mad_i64_i32 v[6:7], s[16:17], v8, s92, v[6:7]
	v_readfirstlane_b32 s16, v164
	s_lshl_b32 s16, s16, 10
	v_ashrrev_i32_e32 v8, 1, v5
	s_add_i32 s16, s16, 0
	v_ashrrev_i32_e32 v9, 31, v8
	s_mov_b32 m0, s16
	v_lshl_add_u64 v[154:155], v[8:9], 1, v[6:7]
	s_add_i32 s17, s16, 0x8000
	global_load_lds_dwordx4 v[150:151], off
	s_add_i32 m0, s16, 0x2000
	v_lshl_add_u64 v[6:7], v[154:155], 0, s[26:27]
	global_load_lds_dwordx4 v[152:153], off
	s_mov_b32 m0, s17
	v_cmp_lt_i32_e32 vcc, 3, v164
	global_load_lds_dwordx4 v[6:7], off
	s_waitcnt vmcnt(0)
	s_waitcnt vmcnt(0) lgkmcnt(0)
	s_barrier
	s_and_saveexec_b64 s[66:67], vcc
	s_cbranch_execz .Lprio_skip_1
	s_setprio 1
.Lprio_skip_1:
	s_or_b64 exec, exec, s[66:67]
	s_xor_b64 s[66:67], s[0:1], -1
	v_and_b32_e32 v5, 0x3fffffc0, v161
	s_add_i32 s0, 0, 0x14000
	v_lshl_add_u32 v168, v5, 2, s0
	s_add_i32 s0, 0, 0x8000
	s_cmp_lg_u32 s0, -1
	v_lshlrev_b32_e32 v5, 1, v162
	v_and_b32_e32 v4, 0x100, v4
	s_cselect_b32 s0, s0, 0
	v_and_b32_e32 v3, 0xc0, v3
	s_cmp_lg_u32 0, -1
	v_and_b32_e32 v5, 32, v5
	v_lshlrev_b32_e32 v167, 2, v166
	v_or3_b32 v2, v3, v4, v2
	s_cselect_b32 s36, 0, 0
	v_lshlrev_b32_e32 v6, 3, v165
	v_add3_u32 v174, v5, s36, v2
	v_add_u32_e32 v2, s33, v167
	v_bitop3_b32 v6, v0, v6, s34 bitop3:0x78
	v_lshl_add_u32 v7, v165, 7, s0
	v_sub_u32_e32 v2, v2, v165
	v_mov_b32_e32 v16, v1
	v_mov_b32_e32 v17, v1
	v_add_u32_e32 v170, v6, v7
	v_xad_u32 v171, v6, 32, v7
	v_xad_u32 v172, v6, 64, v7
	v_xad_u32 v173, v6, s13, v7
	v_sub_u32_e32 v175, v2, v163
	v_mov_b32_e32 v2, v1
	v_mov_b32_e32 v3, v1
	v_mov_b32_e32 v4, v1
	v_mov_b32_e32 v5, v1
	v_mov_b32_e32 v6, v1
	v_mov_b32_e32 v7, v1
	v_mov_b32_e32 v8, v1
	v_mov_b32_e32 v9, v1
	v_mov_b32_e32 v10, v1
	v_mov_b32_e32 v11, v1
	v_mov_b32_e32 v12, v1
	v_mov_b32_e32 v13, v1
	v_mov_b32_e32 v14, v1
	v_mov_b32_e32 v15, v1
	v_mov_b64_e32 v[64:65], v[16:17]
	v_mov_b64_e32 v[48:49], v[16:17]
	v_mov_b64_e32 v[32:33], v[16:17]
	s_mov_b32 s17, 0
	s_mov_b32 s35, 64
	v_cmp_gt_u32_e64 s[0:1], 32, v162
	v_lshl_add_u32 v169, v165, 2, v168
	v_sub_u32_e32 v176, s33, v163
	v_mov_b32_e32 v177, 0xf149f2ca
	v_mov_b32_e32 v178, 0
	v_mov_b64_e32 v[62:63], v[14:15]
	v_mov_b64_e32 v[60:61], v[12:13]
	v_mov_b64_e32 v[58:59], v[10:11]
	v_mov_b64_e32 v[56:57], v[8:9]
	v_mov_b64_e32 v[54:55], v[6:7]
	v_mov_b64_e32 v[52:53], v[4:5]
	v_mov_b64_e32 v[50:51], v[2:3]
	v_mov_b64_e32 v[46:47], v[14:15]
	v_mov_b64_e32 v[44:45], v[12:13]
	v_mov_b64_e32 v[42:43], v[10:11]
	v_mov_b64_e32 v[40:41], v[8:9]
	v_mov_b64_e32 v[38:39], v[6:7]
	v_mov_b64_e32 v[36:37], v[4:5]
	v_mov_b64_e32 v[34:35], v[2:3]
	v_mov_b64_e32 v[30:31], v[14:15]
	v_mov_b64_e32 v[28:29], v[12:13]
	v_mov_b64_e32 v[26:27], v[10:11]
	v_mov_b64_e32 v[24:25], v[8:9]
	v_mov_b64_e32 v[22:23], v[6:7]
	v_mov_b64_e32 v[20:21], v[4:5]
	v_mov_b64_e32 v[18:19], v[2:3]

; template <int DQK, int MODE>
; DI void attn_body(const AttnArgs& a, char* lds) {
;     ...
;     auto finishSM = [&](f32x16& p0, f32x16& p1, float alpha, bf16x8& pa0, bf16x8& pa1, bf16x8& pa2, bf16x8& pa3) {
; #pragma unroll
;         for (int r = 0; r < 16; ++r) p1[r] = __builtin_amdgcn_exp2f(p1[r]);
;         float ps = 0;
; #pragma unroll
;         for (int r = 0; r < 16; ++r) ps += p0[r];
; #pragma unroll
;         for (int r = 0; r < 16; ++r) ps += p1[r];
;         { auto rr = __builtin_amdgcn_permlane32_swap(__float_as_uint(ps), __float_as_uint(ps), false, false);
;           ps = __uint_as_float(rr[0]) + __uint_as_float(rr[1]); }
;         l_reg = l_reg * alpha + ps;
;     ...
;         PK4(p0, 0, pa0); PK4(p0, 8, pa1); PK4(p1, 0, pa2); PK4(p1, 8, pa3);
.LBB0_748:
	s_or_b64 exec, exec, s[68:69]
	s_nop 0
	v_exp_f32_e32 v66, v98
	v_exp_f32_e32 v67, v99
	v_exp_f32_e32 v68, v100
	v_exp_f32_e32 v69, v101
	v_exp_f32_e32 v70, v102
	v_add_f32_e32 v78, 0, v66
	v_exp_f32_e32 v71, v103
	v_add_f32_e32 v78, v67, v78
	v_exp_f32_e32 v72, v104
	v_add_f32_e32 v78, v68, v78
	v_exp_f32_e32 v73, v105
	v_add_f32_e32 v78, v69, v78
	v_exp_f32_e32 v74, v106
	v_add_f32_e32 v78, v70, v78
	v_exp_f32_e32 v75, v107
	v_add_f32_e32 v78, v71, v78
	v_exp_f32_e32 v76, v108
	v_add_f32_e32 v78, v72, v78
	v_exp_f32_e32 v77, v109
	v_add_f32_e32 v78, v73, v78
	v_exp_f32_e32 v84, v110
	v_add_f32_e32 v78, v74, v78
	v_exp_f32_e32 v85, v111
	v_add_f32_e32 v78, v75, v78
	v_exp_f32_e32 v86, v112
	v_add_f32_e32 v78, v76, v78
	v_exp_f32_e32 v87, v113
	v_add_f32_e32 v78, v77, v78
	v_exp_f32_e32 v88, v114
	v_add_f32_e32 v78, v84, v78
	v_exp_f32_e32 v89, v115
	v_add_f32_e32 v78, v85, v78
	v_exp_f32_e32 v90, v116
	v_add_f32_e32 v78, v86, v78
	v_exp_f32_e32 v91, v117
	v_add_f32_e32 v78, v87, v78
	v_exp_f32_e32 v92, v118
	v_add_f32_e32 v78, v88, v78
	v_exp_f32_e32 v93, v119
	v_add_f32_e32 v78, v89, v78
	v_exp_f32_e32 v94, v120
	v_add_f32_e32 v78, v90, v78
	v_exp_f32_e32 v95, v121
	v_add_f32_e32 v78, v91, v78
	v_exp_f32_e32 v96, v122
	v_add_f32_e32 v78, v92, v78
	v_exp_f32_e32 v97, v123
	v_add_f32_e32 v78, v93, v78
	v_exp_f32_e32 v98, v124
	v_add_f32_e32 v78, v94, v78
	v_exp_f32_e32 v99, v125
	v_add_f32_e32 v78, v95, v78
	v_exp_f32_e32 v100, v126
	v_add_f32_e32 v78, v96, v78
	v_exp_f32_e32 v101, v127
	v_add_f32_e32 v78, v97, v78
	v_exp_f32_e32 v102, v128
	v_add_f32_e32 v78, v98, v78
	v_exp_f32_e32 v103, v129
	v_add_f32_e32 v78, v99, v78
	v_add_f32_e32 v78, v100, v78
	v_add_f32_e32 v78, v101, v78
	v_add_f32_e32 v78, v102, v78
	v_add_f32_e32 v82, v103, v78
	v_mov_b32_e32 v83, v82
	v_cvt_pk_bf16_f32 v78, v66, v67
	v_cvt_pk_bf16_f32 v79, v68, v69
	v_cvt_pk_bf16_f32 v80, v70, v71
	v_cvt_pk_bf16_f32 v81, v72, v73
	v_cvt_pk_bf16_f32 v74, v74, v75
	v_cvt_pk_bf16_f32 v75, v76, v77
	v_cvt_pk_bf16_f32 v76, v84, v85
	v_cvt_pk_bf16_f32 v77, v86, v87
	v_cvt_pk_bf16_f32 v70, v88, v89
	v_cvt_pk_bf16_f32 v71, v90, v91
	v_cvt_pk_bf16_f32 v72, v92, v93
	v_cvt_pk_bf16_f32 v73, v94, v95
	v_cvt_pk_bf16_f32 v66, v96, v97
	v_cvt_pk_bf16_f32 v67, v98, v99
	v_cvt_pk_bf16_f32 v68, v100, v101
	v_cvt_pk_bf16_f32 v69, v102, v103
	s_nop 1
	v_permlane32_swap_b32_e32 v82, v83
	v_cmp_gt_f32_e32 vcc, 1.0, v179
	s_cbranch_vccz .LBB0_752
	s_and_saveexec_b64 s[68:69], s[0:1]
	ds_write_b32 v169, v179 offset:128
	s_or_b64 exec, exec, s[68:69]
	s_waitcnt lgkmcnt(0)
	v_add_u32_e32 v96, v168, v0
	ds_read_b128 v[84:87], v96 offset:224
	ds_read_b128 v[88:91], v96 offset:192
	ds_read_b128 v[92:95], v96 offset:160
	ds_read_b128 v[96:99], v96 offset:128
	s_waitcnt lgkmcnt(0)
	v_pk_mul_f32 v[14:15], v[14:15], v[84:85]
	v_pk_mul_f32 v[10:11], v[10:11], v[88:89]
	v_pk_mul_f32 v[6:7], v[6:7], v[92:93]
	v_pk_mul_f32 v[16:17], v[16:17], v[86:87]
	v_pk_mul_f32 v[12:13], v[12:13], v[90:91]
	v_pk_mul_f32 v[8:9], v[8:9], v[94:95]
	v_pk_mul_f32 v[4:5], v[4:5], v[98:99]
	v_pk_mul_f32 v[2:3], v[2:3], v[96:97]
	v_pk_mul_f32 v[62:63], v[62:63], v[84:85]
	v_pk_mul_f32 v[58:59], v[58:59], v[88:89]
	v_pk_mul_f32 v[54:55], v[54:55], v[92:93]
	v_pk_mul_f32 v[64:65], v[64:65], v[86:87]
	v_pk_mul_f32 v[60:61], v[60:61], v[90:91]
	v_pk_mul_f32 v[56:57], v[56:57], v[94:95]
	v_pk_mul_f32 v[52:53], v[52:53], v[98:99]
	v_pk_mul_f32 v[50:51], v[50:51], v[96:97]
	v_pk_mul_f32 v[46:47], v[46:47], v[84:85]
	v_pk_mul_f32 v[42:43], v[42:43], v[88:89]
	v_pk_mul_f32 v[38:39], v[38:39], v[92:93]
	v_pk_mul_f32 v[48:49], v[48:49], v[86:87]
	v_pk_mul_f32 v[44:45], v[44:45], v[90:91]
	v_pk_mul_f32 v[40:41], v[40:41], v[94:95]
	v_pk_mul_f32 v[36:37], v[36:37], v[98:99]
	v_pk_mul_f32 v[34:35], v[34:35], v[96:97]
	v_pk_mul_f32 v[30:31], v[30:31], v[84:85]
	v_pk_mul_f32 v[26:27], v[26:27], v[88:89]
	v_pk_mul_f32 v[22:23], v[22:23], v[92:93]
	v_pk_mul_f32 v[32:33], v[32:33], v[86:87]
	v_pk_mul_f32 v[28:29], v[28:29], v[90:91]
	v_pk_mul_f32 v[24:25], v[24:25], v[94:95]
	v_pk_mul_f32 v[20:21], v[20:21], v[98:99]
	v_pk_mul_f32 v[18:19], v[18:19], v[96:97]

; DI float bf2f(unsigned short b) { return __uint_as_float(((unsigned)b) << 16); }
; DI unsigned short f2bf(float f) { return (unsigned short)(cvtpk(f, f) & 0xffffu); }
; template <int DQK, int MODE>
; DI void attn_body(const AttnArgs& a, char* lds) {
;     ...
;     const bf16_t* Qw = a.Q + (size_t)(wid * 32 + r32) * a.ldq + hi * 8;
; #pragma unroll
;     for (int d0 = 0; d0 < NQR; ++d0) qr[d0] = *(const bf16x8*)(Qw + d0 * 16);
;     if constexpr (MODE == 2) {
;         const f32x2* rp = a.rope + (size_t)(a.qpos0 + wid * 32 + r32) * 32 + hi * 8;
; #pragma unroll
;         for (int dd = 0; dd < 2; ++dd) {
;             bf16x8 x1 = *(const bf16x8*)(Qw + (8 + dd) * 16), x2 = *(const bf16x8*)(Qw + (10 + dd) * 16); bf16x8 y1, y2;
; #pragma unroll
;             for (int j = 0; j < 8; ++j) { const f32x2 cs = rp[dd * 16 + j]; const float a1 = bf2f((unsigned short)x1[j]), a2 = bf2f((unsigned short)x2[j]);
;                 y1[j] = (short)f2bf(a1 * cs.x - a2 * cs.y); y2[j] = (short)f2bf(a1 * cs.y + a2 * cs.x); }
;             *(bf16x8*)(qrl + (8 + dd - NQR) * 1024) = y1; *(bf16x8*)(qrl + (10 + dd - NQR) * 1024) = y2; }
; template <int TYPE>
; DI void attn_phase(const Params& P, int l, unsigned char* shm, const int rep, const bool cross = false) {
;     ...
;         __syncthreads();
;         if (tid_ == 0) *sidx = atomicAdd(ctl + (l * 4 + (cross ? 3 : TYPE)) * 2 + rep, 1);
;         __syncthreads();
;         const int idx = *sidx;
;         if (idx >= (cross ? 256 : 512)) break;
;         const bool sample = idx < 256; const int w = idx & 255, head = w >> 5, qbl = w & 31;
;         const int t0 = (sample ? 32 + qbl : qbl) * 256;
;         const int seqstart = sample ? 8192 : (qbl < 16 ? 0 : 4096), seqlen = sample ? 8192 : 4096;
;         AttnArgs a; a.tid = tid_; a.qpos0 = t0 - seqstart; a.seq = seqlen; a.tab = tab; a.rope = nullptr; a.K2 = nullptr; a.ldk2 = 0; a.map = 0; a.lam = 0.f; a.ga = nullptr; a.oscale = 1.f;
.LBB0_767:
	s_or_b64 exec, exec, s[4:5]
	v_mov_b32_e32 v0, s88
	s_waitcnt lgkmcnt(0)
	s_barrier
	ds_read_b32 v0, v0
	s_mov_b64 s[4:5], -1
	s_waitcnt lgkmcnt(0)
	v_cmp_lt_i32_e32 vcc, s48, v0
	v_readfirstlane_b32 s10, v0
	s_cbranch_vccnz .LBB0_762
	s_lshl_b32 s4, s10, 8
	s_and_b32 s16, s4, 0x1f00
	s_bfe_u32 s28, s10, 0x30005
	s_or_b32 s17, s16, 0x2000
	s_and_b32 s20, s4, 0x1000
	s_cmpk_lt_i32 s10, 0x100
	s_cselect_b64 s[4:5], -1, 0
	s_and_b64 s[10:11], s[4:5], exec
	s_cselect_b32 s29, s17, s16
	s_cselect_b32 s20, 0x2000, s20
	s_sub_i32 s33, s29, s20
	s_mul_i32 s10, s29, 0xc00
	s_add_u32 s10, s24, s10
	s_addc_u32 s11, s25, 0
	s_mul_i32 s16, s28, 0x180
	v_mov_b32_e32 v133, v132
	s_add_u32 s16, s10, s16
	s_addc_u32 s17, s11, 0
	v_ashrrev_i32_e32 v15, 6, v133
	v_and_b32_e32 v136, 31, v133
	v_lshlrev_b32_e32 v135, 5, v15
	v_bfe_u32 v137, v133, 5, 1
	v_or_b32_e32 v0, v135, v136
	v_mov_b64_e32 v[2:3], s[16:17]
	s_movk_i32 s16, 0xc00
	v_mad_i64_i32 v[2:3], s[16:17], v0, s16, v[2:3]
	v_lshlrev_b32_e32 v114, 4, v137
	v_mov_b32_e32 v115, v1
	v_lshl_add_u64 v[10:11], v[2:3], 0, v[114:115]
	v_add_u32_e32 v2, s33, v0
	v_ashrrev_i32_e32 v3, 31, v2
	v_lshlrev_b64 v[2:3], 8, v[2:3]
	v_lshl_add_u64 v[2:3], s[8:9], 0, v[2:3]
	v_lshlrev_b32_e32 v0, 6, v137
	s_barrier
	global_load_dwordx4 v[98:101], v[10:11], off
	global_load_dwordx4 v[102:105], v[10:11], off offset:32
	global_load_dwordx4 v[106:109], v[10:11], off offset:64
	global_load_dwordx4 v[110:113], v[10:11], off offset:96
	v_lshl_add_u64 v[12:13], v[2:3], 0, v[0:1]
	global_load_dwordx4 v[2:5], v[10:11], off offset:256
	global_load_dwordx4 v[6:9], v[10:11], off offset:320
	global_load_dwordx2 v[16:17], v[12:13], off
	v_and_b32_e32 v134, 63, v133
	v_lshlrev_b32_e32 v138, 13, v15
	v_lshlrev_b32_e32 v14, 4, v134
	s_mov_b32 s16, 0x5040100
	v_add3_u32 v139, s49, v138, v14
	s_lshl_b32 s10, s20, 12
	s_add_u32 s10, s15, s10
	s_addc_u32 s11, s22, 0
	s_lshl_b32 s35, s28, 9
	s_add_u32 s10, s10, s35
	s_addc_u32 s11, s11, 0
	s_mulk_i32 s20, 0x5c00
	s_add_u32 s20, s14, s20
	s_addc_u32 s35, s12, 0
	s_add_u32 s50, s20, 0x4c82a00
	s_addc_u32 s51, s35, 0
	s_waitcnt vmcnt(2)
	v_lshlrev_b32_e32 v19, 16, v2
	s_waitcnt vmcnt(1)
	v_lshlrev_b32_e32 v18, 16, v6
	s_waitcnt vmcnt(0)
	v_pk_mul_f32 v[20:21], v[16:17], v[18:19] op_sel:[0,1] op_sel_hi:[1,0]
	v_pk_mul_f32 v[16:17], v[16:17], v[18:19]
	v_sub_f32_e32 v0, v20, v21
	v_add_f32_e32 v16, v17, v16
	v_cvt_pk_bf16_f32 v0, v0, v0
	v_cvt_pk_bf16_f32 v22, v16, v16
	global_load_dwordx2 v[16:17], v[12:13], off offset:8
	v_and_b32_e32 v19, 0xffff0000, v2
	v_and_b32_e32 v18, 0xffff0000, v6
	s_waitcnt vmcnt(0)
	v_pk_mul_f32 v[20:21], v[16:17], v[18:19] op_sel:[0,1] op_sel_hi:[1,0]
	s_nop 0
	v_sub_f32_e32 v2, v20, v21
	v_pk_mul_f32 v[16:17], v[16:17], v[18:19]
	v_cvt_pk_bf16_f32 v23, v2, v2
	v_lshlrev_b32_e32 v19, 16, v3
	v_add_f32_e32 v2, v17, v16
	v_cvt_pk_bf16_f32 v24, v2, v2
	global_load_dwordx2 v[16:17], v[12:13], off offset:16
	v_lshlrev_b32_e32 v18, 16, v7
	v_and_b32_e32 v3, 0xffff0000, v3
	s_waitcnt vmcnt(0)
	v_pk_mul_f32 v[20:21], v[16:17], v[18:19] op_sel:[0,1] op_sel_hi:[1,0]
	s_nop 0
	v_sub_f32_e32 v2, v20, v21
	v_pk_mul_f32 v[16:17], v[16:17], v[18:19]
	v_cvt_pk_bf16_f32 v20, v2, v2
	s_nop 0
	v_add_f32_e32 v2, v17, v16
	v_cvt_pk_bf16_f32 v18, v2, v2
	global_load_dwordx2 v[16:17], v[12:13], off offset:24
	v_and_b32_e32 v2, 0xffff0000, v7
	s_waitcnt vmcnt(0)
	v_pk_mul_f32 v[6:7], v[16:17], v[2:3] op_sel:[0,1] op_sel_hi:[1,0]
	v_pk_mul_f32 v[2:3], v[16:17], v[2:3]
	v_sub_f32_e32 v6, v6, v7
	v_add_f32_e32 v2, v3, v2
	v_cvt_pk_bf16_f32 v19, v6, v6
	v_cvt_pk_bf16_f32 v21, v2, v2
	global_load_dwordx2 v[2:3], v[12:13], off offset:32
	v_lshlrev_b32_e32 v7, 16, v4
	v_lshlrev_b32_e32 v6, 16, v8
	s_waitcnt vmcnt(0)
	v_pk_mul_f32 v[16:17], v[2:3], v[6:7] op_sel:[0,1] op_sel_hi:[1,0]
	v_pk_mul_f32 v[2:3], v[2:3], v[6:7]
	v_sub_f32_e32 v16, v16, v17
	v_add_f32_e32 v2, v3, v2
	v_cvt_pk_bf16_f32 v25, v16, v16
	v_cvt_pk_bf16_f32 v26, v2, v2
	global_load_dwordx2 v[2:3], v[12:13], off offset:40
	v_and_b32_e32 v7, 0xffff0000, v4
	v_and_b32_e32 v6, 0xffff0000, v8
	s_waitcnt vmcnt(0)
	v_pk_mul_f32 v[16:17], v[2:3], v[6:7] op_sel:[0,1] op_sel_hi:[1,0]
	v_pk_mul_f32 v[2:3], v[2:3], v[6:7]
	v_sub_f32_e32 v4, v16, v17
	v_add_f32_e32 v2, v3, v2
	v_cvt_pk_bf16_f32 v4, v4, v4
	v_cvt_pk_bf16_f32 v8, v2, v2
	global_load_dwordx2 v[2:3], v[12:13], off offset:48
	v_lshlrev_b32_e32 v7, 16, v5
	v_lshlrev_b32_e32 v6, 16, v9
	v_perm_b32 v4, v4, v25, s16
	v_perm_b32 v8, v8, v26, s16
	s_waitcnt vmcnt(0)
	v_pk_mul_f32 v[16:17], v[2:3], v[6:7] op_sel:[0,1] op_sel_hi:[1,0]
	v_pk_mul_f32 v[2:3], v[2:3], v[6:7]
	v_sub_f32_e32 v16, v16, v17
	v_cvt_pk_bf16_f32 v27, v16, v16
	v_add_f32_e32 v2, v3, v2
	v_cvt_pk_bf16_f32 v28, v2, v2
	global_load_dwordx2 v[6:7], v[12:13], off offset:56
	v_and_b32_e32 v17, 0xffff0000, v5
	v_and_b32_e32 v16, 0xffff0000, v9
	s_waitcnt vmcnt(0)
	v_pk_mul_f32 v[2:3], v[6:7], v[16:17] op_sel:[0,1] op_sel_hi:[1,0]
	s_nop 0
	v_sub_f32_e32 v2, v2, v3
	v_cvt_pk_bf16_f32 v5, v2, v2
	v_pk_mul_f32 v[6:7], v[6:7], v[16:17]
	v_perm_b32 v2, v23, v0, s16
	v_perm_b32 v3, v19, v20, s16
	v_perm_b32 v5, v5, v27, s16
	v_add_f32_e32 v0, v7, v6
	v_cvt_pk_bf16_f32 v0, v0, v0
	v_perm_b32 v6, v24, v22, s16
	v_perm_b32 v7, v21, v18, s16
	v_perm_b32 v9, v0, v28, s16
	ds_write_b128 v139, v[2:5] offset:4096
	ds_write_b128 v139, v[6:9] offset:6144
	global_load_dwordx4 v[2:5], v[10:11], off offset:288
	global_load_dwordx4 v[6:9], v[10:11], off offset:352
	global_load_dwordx2 v[16:17], v[12:13], off offset:128
	s_waitcnt vmcnt(2)
	v_lshlrev_b32_e32 v19, 16, v2
	s_waitcnt vmcnt(1)
	v_lshlrev_b32_e32 v18, 16, v6
	s_waitcnt vmcnt(0)
; DI float bf2f(unsigned short b) { return __uint_as_float(((unsigned)b) << 16); }
; DI unsigned short f2bf(float f) { return (unsigned short)(cvtpk(f, f) & 0xffffu); }
; template <int DQK, int MODE>
; DI void attn_body(const AttnArgs& a, char* lds) {
;     ...
; #pragma unroll
;         for (int dd = 0; dd < 2; ++dd) {
;             bf16x8 x1 = *(const bf16x8*)(Qw + (8 + dd) * 16), x2 = *(const bf16x8*)(Qw + (10 + dd) * 16); bf16x8 y1, y2;
; #pragma unroll
;             for (int j = 0; j < 8; ++j) { const f32x2 cs = rp[dd * 16 + j]; const float a1 = bf2f((unsigned short)x1[j]), a2 = bf2f((unsigned short)x2[j]);
;                 y1[j] = (short)f2bf(a1 * cs.x - a2 * cs.y); y2[j] = (short)f2bf(a1 * cs.y + a2 * cs.x); }
;             *(bf16x8*)(qrl + (8 + dd - NQR) * 1024) = y1; *(bf16x8*)(qrl + (10 + dd - NQR) * 1024) = y2; }
; #pragma unroll
;         for (int d0 = NQR; d0 < 8; ++d0) *(bf16x8*)(qrl + (d0 - NQR) * 1024) = *(const bf16x8*)(Qw + d0 * 16);
	v_pk_mul_f32 v[20:21], v[16:17], v[18:19] op_sel:[0,1] op_sel_hi:[1,0]
	v_pk_mul_f32 v[16:17], v[16:17], v[18:19]
	v_sub_f32_e32 v0, v20, v21
	v_add_f32_e32 v16, v17, v16
	v_cvt_pk_bf16_f32 v0, v0, v0
	v_cvt_pk_bf16_f32 v22, v16, v16
	global_load_dwordx2 v[16:17], v[12:13], off offset:136
	v_and_b32_e32 v19, 0xffff0000, v2
	v_and_b32_e32 v18, 0xffff0000, v6
	s_waitcnt vmcnt(0)
	v_pk_mul_f32 v[20:21], v[16:17], v[18:19] op_sel:[0,1] op_sel_hi:[1,0]
	s_nop 0
	v_sub_f32_e32 v2, v20, v21
	v_pk_mul_f32 v[16:17], v[16:17], v[18:19]
	v_cvt_pk_bf16_f32 v23, v2, v2
	v_lshlrev_b32_e32 v19, 16, v3
	v_add_f32_e32 v2, v17, v16
	v_cvt_pk_bf16_f32 v24, v2, v2
	global_load_dwordx2 v[16:17], v[12:13], off offset:144
	v_lshlrev_b32_e32 v18, 16, v7
	v_and_b32_e32 v3, 0xffff0000, v3
	s_waitcnt vmcnt(0)
	v_pk_mul_f32 v[20:21], v[16:17], v[18:19] op_sel:[0,1] op_sel_hi:[1,0]
	s_nop 0
	v_sub_f32_e32 v2, v20, v21
	v_pk_mul_f32 v[16:17], v[16:17], v[18:19]
	v_cvt_pk_bf16_f32 v20, v2, v2
	s_nop 0
	v_add_f32_e32 v2, v17, v16
	v_cvt_pk_bf16_f32 v18, v2, v2
	global_load_dwordx2 v[16:17], v[12:13], off offset:152
	v_and_b32_e32 v2, 0xffff0000, v7
	s_waitcnt vmcnt(0)
	v_pk_mul_f32 v[6:7], v[16:17], v[2:3] op_sel:[0,1] op_sel_hi:[1,0]
	v_pk_mul_f32 v[2:3], v[16:17], v[2:3]
	v_sub_f32_e32 v6, v6, v7
	v_add_f32_e32 v2, v3, v2
	v_cvt_pk_bf16_f32 v19, v6, v6
	v_cvt_pk_bf16_f32 v21, v2, v2
	global_load_dwordx2 v[2:3], v[12:13], off offset:160
	v_lshlrev_b32_e32 v7, 16, v4
	v_lshlrev_b32_e32 v6, 16, v8
	s_waitcnt vmcnt(0)
	v_pk_mul_f32 v[16:17], v[2:3], v[6:7] op_sel:[0,1] op_sel_hi:[1,0]
	v_pk_mul_f32 v[2:3], v[2:3], v[6:7]
	v_sub_f32_e32 v16, v16, v17
	v_add_f32_e32 v2, v3, v2
	v_cvt_pk_bf16_f32 v25, v16, v16
	v_cvt_pk_bf16_f32 v26, v2, v2
	global_load_dwordx2 v[2:3], v[12:13], off offset:168
	v_and_b32_e32 v7, 0xffff0000, v4
	v_and_b32_e32 v6, 0xffff0000, v8
	s_waitcnt vmcnt(0)
	v_pk_mul_f32 v[16:17], v[2:3], v[6:7] op_sel:[0,1] op_sel_hi:[1,0]
	v_pk_mul_f32 v[2:3], v[2:3], v[6:7]
	v_sub_f32_e32 v4, v16, v17
	v_add_f32_e32 v2, v3, v2
	v_cvt_pk_bf16_f32 v4, v4, v4
	v_cvt_pk_bf16_f32 v8, v2, v2
	global_load_dwordx2 v[2:3], v[12:13], off offset:176
	v_lshlrev_b32_e32 v7, 16, v5
	v_lshlrev_b32_e32 v6, 16, v9
	v_perm_b32 v4, v4, v25, s16
	v_perm_b32 v8, v8, v26, s16
	s_waitcnt vmcnt(0)
	v_pk_mul_f32 v[16:17], v[2:3], v[6:7] op_sel:[0,1] op_sel_hi:[1,0]
	s_nop 0
	v_sub_f32_e32 v16, v16, v17
	v_pk_mul_f32 v[2:3], v[2:3], v[6:7]
	v_cvt_pk_bf16_f32 v16, v16, v16
	s_nop 0
	v_add_f32_e32 v2, v3, v2
	v_cvt_pk_bf16_f32 v17, v2, v2
	global_load_dwordx2 v[6:7], v[12:13], off offset:184
	v_and_b32_e32 v13, 0xffff0000, v5
	v_and_b32_e32 v12, 0xffff0000, v9
	s_waitcnt vmcnt(0)
	v_pk_mul_f32 v[2:3], v[6:7], v[12:13] op_sel:[0,1] op_sel_hi:[1,0]
	s_nop 0
	v_sub_f32_e32 v2, v2, v3
	v_cvt_pk_bf16_f32 v5, v2, v2
	v_pk_mul_f32 v[6:7], v[6:7], v[12:13]
	v_perm_b32 v2, v23, v0, s16
	v_perm_b32 v3, v19, v20, s16
	v_perm_b32 v5, v5, v16, s16
	v_add_f32_e32 v0, v7, v6
	v_cvt_pk_bf16_f32 v0, v0, v0
	v_perm_b32 v6, v24, v22, s16
	v_perm_b32 v7, v21, v18, s16
	v_perm_b32 v9, v0, v17, s16
	ds_write_b128 v139, v[2:5] offset:5120
	ds_write_b128 v139, v[6:9] offset:7168
	global_load_dwordx4 v[2:5], v[10:11], off offset:128
	s_waitcnt vmcnt(0)
	ds_write_b128 v139, v[2:5]
	global_load_dwordx4 v[2:5], v[10:11], off offset:160
	s_waitcnt vmcnt(0)
	ds_write_b128 v139, v[2:5] offset:1024
	global_load_dwordx4 v[2:5], v[10:11], off offset:192
	s_waitcnt vmcnt(0)
	ds_write_b128 v139, v[2:5] offset:2048
	global_load_dwordx4 v[2:5], v[10:11], off offset:224
	s_waitcnt vmcnt(0)
; #define DMA(buf, k0) do { _Pragma("unroll") for (int _i = 0; _i < NI; ++_i) { \
;         char* _d = (_i < 2) ? V_lds + (buf) * SHM_V + (wu + 8 * _i) * 1024 : K_lds + (buf) * SHM_K + (wu + 8 * _i - 16) * 1024; \
;         __builtin_amdgcn_global_load_lds((const unsigned*)(sp[_i] + (size_t)(k0) * sld[_i]), (LAS unsigned*)_d, 16, 0, 0); } } while (0)
; template <int DQK, int MODE>
; DI void attn_body(const AttnArgs& a, char* lds) {
;     ...
;     constexpr int NI = 2 + KCH;
;     const bf16_t* sp[NI]; int sld[NI];
; #pragma unroll
;     for (int i = 0; i < NI; ++i) { const int b = wid + 8 * i;
;         if (i < 2) { const int pos = b * 1024 + lane * 16, stl = pos >> 9, q = (pos & 511) >> 1, kk = (stl >> 2) * 8 + (q >> 5), c = (stl & 3) * 32 + (q & 31);
;             const int k = (kk & ~0xC) | ((kk & 4) << 1) | ((kk & 8) >> 1);
;             sp[i] = a.V + (size_t)k * a.ldv + c; sld[i] = a.ldv;
;         } else { const int pos = (b - 16) * 1024 + lane * 16, row = pos / KROWB, within = pos - row * KROWB, c = (within ^ ksw(row)) >> 4;
;             if (MODE == 2 && c >= 16) { sp[i] = a.K2 + (size_t)row * a.ldk2 + (c - 16) * 8; sld[i] = a.ldk2; }
;             else { sp[i] = a.K + (size_t)row * a.ldk + c * 8; sld[i] = a.ldk; } } }
;     const int wu = __builtin_amdgcn_readfirstlane(wid);
;     ...
;     constexpr int NB = (KROWB == 256) ? 8 : 4;
;     int kb[NB];
;     { const int X = (hi * 16) ^ ksw(r32);
; #pragma unroll
;       for (int i = 0; i < NB; ++i) kb[i] = (int)(uintptr_t)K_lds + r32 * KROWB + ((i * 32) ^ X); }
;     const int qra = (int)(uintptr_t)qrl;
;     ...
;     DMA(0, 0); asm volatile("s_waitcnt vmcnt(0)" ::: "memory"); __syncthreads();
;     if (wid >= 4) __builtin_amdgcn_s_setprio(1);
	ds_write_b128 v139, v[2:5] offset:3072
	v_lshl_or_b32 v4, v15, 10, v14
	v_mul_hi_i32 v0, v4, s47
	v_lshrrev_b32_e32 v2, 31, v0
	v_ashrrev_i32_e32 v0, 6, v0
	v_add_u32_e32 v2, v0, v2
	v_mad_i32_i24 v0, v2, s53, v4
	v_lshlrev_b32_e32 v3, 3, v2
	v_bitop3_b32 v0, v0, v3, s34 bitop3:0x78
	v_cmp_gt_i32_e32 vcc, s56, v0
	v_ashrrev_i32_e32 v3, 31, v2
	s_and_saveexec_b64 s[16:17], vcc
	s_xor_b64 s[54:55], exec, s[16:17]
	v_lshlrev_b64 v[2:3], 12, v[2:3]
	v_ashrrev_i32_e32 v6, 1, v0
	v_lshl_add_u64 v[2:3], s[10:11], 0, v[2:3]
	v_ashrrev_i32_e32 v7, 31, v6
	v_lshl_add_u64 v[116:117], v[6:7], 1, v[2:3]
	s_or_saveexec_b64 s[54:55], s[54:55]
	v_mov_b64_e32 v[118:119], 0x800
	s_xor_b64 exec, exec, s[54:55]
	v_mul_hi_i32_i24_e32 v3, 0x5c00, v2
	v_mul_i32_i24_e32 v2, 0x5c00, v2
	v_lshl_add_u64 v[2:3], s[50:51], 0, v[2:3]
	v_lshl_add_u64 v[2:3], v[2:3], 0, v[0:1]
	v_lshl_add_u64 v[116:117], v[2:3], 0, s[60:61]
	v_mov_b64_e32 v[118:119], 0x2e00
	s_or_b64 exec, exec, s[54:55]
	v_add_u32_e32 v4, 0xffffc000, v4
	v_add_u32_e32 v0, 0x6000, v4
	v_mul_hi_i32 v2, v0, s47
	v_lshrrev_b32_e32 v3, 31, v2
	v_ashrrev_i32_e32 v2, 6, v2
	v_add_u32_e32 v2, v2, v3
	v_mad_i32_i24 v0, v2, s53, v0
	v_lshlrev_b32_e32 v3, 3, v2
	v_bitop3_b32 v0, v0, v3, s34 bitop3:0x78
	v_cmp_gt_i32_e32 vcc, s56, v0
	v_ashrrev_i32_e32 v3, 31, v2
	s_and_saveexec_b64 s[16:17], vcc
	s_xor_b64 s[54:55], exec, s[16:17]
	v_lshlrev_b64 v[2:3], 12, v[2:3]
	v_ashrrev_i32_e32 v6, 1, v0
	v_lshl_add_u64 v[2:3], s[10:11], 0, v[2:3]
	v_ashrrev_i32_e32 v7, 31, v6
	v_lshl_add_u64 v[120:121], v[6:7], 1, v[2:3]
	s_or_saveexec_b64 s[54:55], s[54:55]
	v_mov_b64_e32 v[122:123], 0x800
	s_xor_b64 exec, exec, s[54:55]
	v_mul_hi_i32_i24_e32 v3, 0x5c00, v2
	v_mul_i32_i24_e32 v2, 0x5c00, v2
	v_lshl_add_u64 v[2:3], s[50:51], 0, v[2:3]
	v_lshl_add_u64 v[2:3], v[2:3], 0, v[0:1]
	v_lshl_add_u64 v[120:121], v[2:3], 0, s[60:61]
	v_mov_b64_e32 v[122:123], 0x2e00
	s_or_b64 exec, exec, s[54:55]
	v_add_u32_e32 v0, 0x8000, v4
	v_mul_hi_i32 v2, v0, s47
	v_lshrrev_b32_e32 v3, 31, v2
	v_ashrrev_i32_e32 v2, 6, v2
	v_add_u32_e32 v2, v2, v3
	v_mad_i32_i24 v0, v2, s53, v0
	v_lshlrev_b32_e32 v3, 3, v2
	v_bitop3_b32 v0, v0, v3, s34 bitop3:0x78
	v_cmp_gt_i32_e32 vcc, s56, v0
	v_ashrrev_i32_e32 v3, 31, v2
	s_and_saveexec_b64 s[16:17], vcc
	s_xor_b64 s[54:55], exec, s[16:17]
	v_lshlrev_b64 v[2:3], 12, v[2:3]
	v_ashrrev_i32_e32 v4, 1, v0
	v_lshl_add_u64 v[2:3], s[10:11], 0, v[2:3]
	v_ashrrev_i32_e32 v5, 31, v4
	v_lshl_add_u64 v[124:125], v[4:5], 1, v[2:3]
	s_or_saveexec_b64 s[54:55], s[54:55]
	v_mov_b64_e32 v[126:127], 0x800
	s_xor_b64 exec, exec, s[54:55]
	v_mul_hi_i32_i24_e32 v3, 0x5c00, v2
	v_mul_i32_i24_e32 v2, 0x5c00, v2
	v_lshl_add_u64 v[2:3], s[50:51], 0, v[2:3]
	v_lshl_add_u64 v[2:3], v[2:3], 0, v[0:1]
	v_lshl_add_u64 v[124:125], v[2:3], 0, s[60:61]
	v_mov_b64_e32 v[126:127], 0x2e00
	s_or_b64 exec, exec, s[54:55]
	v_lshlrev_b32_e32 v3, 3, v134
	v_and_b32_e32 v2, 24, v3
	v_bfe_u32 v0, v133, 2, 2
	v_and_or_b32 v4, v133, s13, v2
	v_lshrrev_b32_e32 v5, 1, v133
	v_bfe_u32 v8, v133, 2, 3
	v_lshlrev_b32_e32 v0, 1, v4
	v_lshl_add_u64 v[4:5], s[10:11], 0, v[0:1]
	v_lshlrev_b32_e32 v0, 2, v15
	v_lshlrev_b32_e32 v6, 2, v15
	v_and_b32_e32 v0, -16, v0
	v_and_b32_e32 v9, 8, v6
	v_or3_b32 v6, v8, v9, v0
	v_or3_b32 v0, v0, v9, v8
	v_ashrrev_i32_e32 v7, 31, v6
	v_add_u32_e32 v8, 32, v0
	v_readfirstlane_b32 s10, v15
	v_lshlrev_b64 v[6:7], 12, v[6:7]
	v_ashrrev_i32_e32 v9, 31, v8
	s_lshl_b32 s10, s10, 10
	v_lshl_add_u64 v[128:129], v[4:5], 0, v[6:7]
	v_lshlrev_b64 v[8:9], 12, v[8:9]
	s_add_i32 s16, s10, 0
	v_lshl_add_u64 v[6:7], v[128:129], 0, s[58:59]
	v_lshl_add_u64 v[130:131], v[4:5], 0, v[8:9]
	s_mov_b32 m0, s16
	v_lshl_add_u64 v[4:5], v[130:131], 0, s[58:59]
	s_add_i32 s10, s16, 0x8000
	global_load_lds_dwordx4 v[6:7], off
	s_add_i32 m0, s16, 0x2000
	v_cmp_lt_i32_e32 vcc, 3, v15
	global_load_lds_dwordx4 v[4:5], off
	s_mov_b32 m0, s10
	s_nop 0
	global_load_lds_dwordx4 v[116:117], off
	s_add_i32 m0, s16, 0xa000
	s_nop 0
	global_load_lds_dwordx4 v[120:121], off
	s_add_i32 m0, s16, 0xc000
	s_nop 0
	global_load_lds_dwordx4 v[124:125], off
	s_waitcnt vmcnt(0)
	s_waitcnt vmcnt(0) lgkmcnt(0)
	s_barrier
	s_and_saveexec_b64 s[10:11], vcc
	s_cbranch_execz .Lprio_skip_2
	s_setprio 1
.Lprio_skip_2:
	s_or_b64 exec, exec, s[10:11]
	s_add_i32 s10, 0, 0x8000
	s_cmp_lg_u32 s10, -1
	v_mul_u32_u24_e32 v0, 0x180, v136
	v_lshlrev_b32_e32 v4, 3, v136
	s_cselect_b32 s10, s10, 0
	v_bitop3_b32 v4, v114, v4, s34 bitop3:0x78
	v_add_u32_e32 v0, s10, v0
	s_and_b64 s[4:5], s[4:5], exec
	v_add_u32_e32 v119, v4, v0
	v_xad_u32 v123, v4, 32, v0
	v_xad_u32 v127, v4, 64, v0
	v_xad_u32 v140, v4, s13, v0
	s_cselect_b32 s33, 0x80, 64
	v_and_b32_e32 v4, 0x3fffffc0, v133
	s_add_i32 s4, 0, 0x14000
	v_and_b32_e32 v3, 0x100, v3
	v_and_b32_e32 v0, 0xc0, v14
	v_lshl_add_u32 v115, v4, 2, s4
	v_lshlrev_b32_e32 v4, 1, v134
	s_cmp_lg_u32 0, -1
	v_and_b32_e32 v4, 32, v4
	v_or3_b32 v0, v0, v3, v2
	s_cselect_b32 s10, 0, 0
	v_mov_b32_e32 v14, v1
	v_mov_b32_e32 v15, v1
	v_add3_u32 v142, v4, s10, v0
	v_mov_b32_e32 v0, v1
	v_mov_b32_e32 v2, v1
	v_mov_b32_e32 v3, v1
	v_mov_b32_e32 v4, v1
	v_mov_b32_e32 v5, v1
	v_mov_b32_e32 v6, v1
	v_mov_b32_e32 v7, v1
	v_mov_b32_e32 v8, v1
	v_mov_b32_e32 v9, v1
	v_mov_b32_e32 v10, v1
	v_mov_b32_e32 v11, v1
	v_mov_b32_e32 v12, v1
	v_mov_b32_e32 v13, v1
	v_mov_b64_e32 v[64:65], v[14:15]
	v_mov_b64_e32 v[48:49], v[14:15]
	v_mov_b64_e32 v[32:33], v[14:15]
	v_mov_b64_e32 v[62:63], v[12:13]
	v_mov_b64_e32 v[60:61], v[10:11]
	v_mov_b64_e32 v[58:59], v[8:9]
	v_mov_b64_e32 v[56:57], v[6:7]
	v_mov_b64_e32 v[54:55], v[4:5]
	v_mov_b64_e32 v[52:53], v[2:3]
	v_mov_b64_e32 v[50:51], v[0:1]
	v_mov_b64_e32 v[46:47], v[12:13]
	v_mov_b64_e32 v[44:45], v[10:11]
	v_mov_b64_e32 v[42:43], v[8:9]
	v_mov_b64_e32 v[40:41], v[6:7]
	v_mov_b64_e32 v[38:39], v[4:5]
	v_mov_b64_e32 v[36:37], v[2:3]
	v_mov_b64_e32 v[34:35], v[0:1]
	v_mov_b64_e32 v[30:31], v[12:13]
	v_mov_b64_e32 v[28:29], v[10:11]
	v_mov_b64_e32 v[26:27], v[8:9]
	v_mov_b64_e32 v[24:25], v[6:7]
	v_mov_b64_e32 v[22:23], v[4:5]
	v_mov_b64_e32 v[20:21], v[2:3]
	v_mov_b64_e32 v[18:19], v[0:1]
	v_mov_b64_e32 v[16:17], v[14:15]
	s_mov_b32 s17, 0
	s_mov_b32 s20, 64
	v_cmp_gt_u32_e64 s[4:5], 32, v134
	v_lshl_add_u32 v141, v136, 2, v115
	v_mov_b32_e32 v143, 0xf149f2ca
	v_mov_b32_e32 v144, 0
	v_mov_b64_e32 v[14:15], v[12:13]
	v_mov_b64_e32 v[12:13], v[10:11]
	v_mov_b64_e32 v[10:11], v[8:9]
	v_mov_b64_e32 v[8:9], v[6:7]
	v_mov_b64_e32 v[6:7], v[4:5]
	v_mov_b64_e32 v[4:5], v[2:3]
	v_mov_b64_e32 v[2:3], v[0:1]
	s_and_b32 s35, s17, 1
	s_add_i32 s17, s17, 1
	s_cmp_ge_u32 s17, s33
	s_cbranch_scc1 .LBB0_784

; #define SBAR() __builtin_amdgcn_sched_barrier(0)
; template <int I, int N, class F> DI void cfor(F&& f) { if constexpr (I < N) { f(std::integral_constant<int, I>{}); cfor<I + 1, N>(f); } }
; template <int OFF> DI void dsr128(bf16x8& r, int addr) { asm volatile("ds_read_b128 %0, %1 offset:%2" : "=&v"(r) : "v"(addr), "i"(OFF) : "memory"); }
; template <int N> DI void wait_lgkm() { asm volatile("s_waitcnt lgkmcnt(%0)" :: "i"(N) : "memory"); }
; template <int DQK, int MODE>
; DI void attn_body(const AttnArgs& a, char* lds) {
;     ...
;     auto qkt = [&](f32x16& p0, f32x16& p1, const int kofs) {
;         p0 = f32x16{}; p1 = f32x16{};
;         int kc[NB];
; #pragma unroll
;         for (int i = 0; i < NB; ++i) kc[i] = kb[i] + kofs;
;         bf16x8 fk[2][2]; bf16x8 fq[2];
;         auto rd = [&](auto ic) { constexpr int d0 = decltype(ic)::value; constexpr int sl = d0 & 1;
;             dsr128<(d0 / NB) * (NB * 32)>(fk[sl][0], kc[d0 % NB]); dsr128<(d0 / NB) * (NB * 32) + 32 * KROWB>(fk[sl][1], kc[d0 % NB]);
;             if constexpr (MODE == 2 && d0 >= NQR) dsr128<(d0 - NQR) * 1024>(fq[sl], qra); };
;         rd(std::integral_constant<int, 0>{});
;         cfor<0, ND0>([&](auto ic) { constexpr int d0 = decltype(ic)::value; constexpr int sl = d0 & 1;
;             if constexpr (d0 + 1 < ND0) { rd(std::integral_constant<int, d0 + 1>{}); wait_lgkm<(MODE == 2 && d0 + 1 >= NQR) ? 3 : 2>(); }
;             else wait_lgkm<0>();
;             SBAR();
;             bf16x8 qf; if constexpr (MODE == 2 && d0 >= NQR) qf = fq[sl]; else qf = qr[d0 < NQR ? d0 : 0];
;             p0 = __builtin_amdgcn_mfma_f32_32x32x16_bf16(fk[sl][0], qf, p0, 0, 0, 0);
;             p1 = __builtin_amdgcn_mfma_f32_32x32x16_bf16(fk[sl][1], qf, p1, 0, 0, 0); });
;     };
.LBB0_784:
	s_mul_i32 s10, s35, 0x6000
	v_add_u32_e32 v0, s10, v119
	ds_read_b128 v[66:69], v0 offset:0
	ds_read_b128 v[70:73], v0 offset:0x3000
	v_add_u32_e32 v145, s10, v123
	ds_read_b128 v[146:149], v145 offset:0
	ds_read_b128 v[150:153], v145 offset:0x3000
	s_waitcnt lgkmcnt(2)
	v_add_u32_e32 v170, s10, v127
	v_add_u32_e32 v171, s10, v140
	v_mfma_f32_32x32x16_bf16 v[82:97], v[66:69], v[98:101], 0
	ds_read_b128 v[154:157], v170 offset:0
	ds_read_b128 v[158:161], v170 offset:0x3000
	s_waitcnt lgkmcnt(2)
	v_mfma_f32_32x32x16_bf16 v[66:81], v[70:73], v[98:101], 0
	v_mfma_f32_32x32x16_bf16 v[82:97], v[146:149], v[102:105], v[82:97]
	ds_read_b128 v[146:149], v171 offset:0
	v_mfma_f32_32x32x16_bf16 v[66:81], v[150:153], v[102:105], v[66:81]
	ds_read_b128 v[150:153], v171 offset:0x3000
	s_waitcnt lgkmcnt(2)
	v_mfma_f32_32x32x16_bf16 v[82:97], v[154:157], v[106:109], v[82:97]
	ds_read_b128 v[154:157], v0 offset:0x80
	v_mfma_f32_32x32x16_bf16 v[66:81], v[158:161], v[106:109], v[66:81]
	ds_read_b128 v[158:161], v0 offset:0x3080
	ds_read_b128 v[162:165], v139 offset:0
	s_waitcnt lgkmcnt(3)
	v_mfma_f32_32x32x16_bf16 v[82:97], v[146:149], v[110:113], v[82:97]
	ds_read_b128 v[146:149], v145 offset:0x80
	v_mfma_f32_32x32x16_bf16 v[66:81], v[150:153], v[110:113], v[66:81]
	ds_read_b128 v[150:153], v145 offset:0x3080
	ds_read_b128 v[166:169], v139 offset:0x400
	s_waitcnt lgkmcnt(3)
	v_mfma_f32_32x32x16_bf16 v[82:97], v[154:157], v[162:165], v[82:97]
	ds_read_b128 v[154:157], v170 offset:0x80
	v_mfma_f32_32x32x16_bf16 v[66:81], v[158:161], v[162:165], v[66:81]
	ds_read_b128 v[158:161], v170 offset:0x3080
	ds_read_b128 v[162:165], v139 offset:0x800
	s_waitcnt lgkmcnt(3)
	v_mfma_f32_32x32x16_bf16 v[82:97], v[146:149], v[166:169], v[82:97]
	ds_read_b128 v[146:149], v171 offset:0x80
	v_mfma_f32_32x32x16_bf16 v[66:81], v[150:153], v[166:169], v[66:81]
	ds_read_b128 v[150:153], v171 offset:0x3080
	ds_read_b128 v[166:169], v139 offset:0xc00
	s_waitcnt lgkmcnt(3)
	v_mfma_f32_32x32x16_bf16 v[82:97], v[154:157], v[162:165], v[82:97]
	ds_read_b128 v[154:157], v0 offset:0x100
	v_mfma_f32_32x32x16_bf16 v[66:81], v[158:161], v[162:165], v[66:81]
	ds_read_b128 v[158:161], v0 offset:0x3100
	ds_read_b128 v[162:165], v139 offset:0x1000
	s_waitcnt lgkmcnt(3)
	v_mfma_f32_32x32x16_bf16 v[82:97], v[146:149], v[166:169], v[82:97]
	ds_read_b128 v[146:149], v145 offset:0x100
	v_mfma_f32_32x32x16_bf16 v[66:81], v[150:153], v[166:169], v[66:81]
	ds_read_b128 v[150:153], v145 offset:0x3100
	ds_read_b128 v[166:169], v139 offset:0x1400
	s_waitcnt lgkmcnt(3)
	v_mfma_f32_32x32x16_bf16 v[82:97], v[154:157], v[162:165], v[82:97]
	ds_read_b128 v[154:157], v170 offset:0x100
	v_mfma_f32_32x32x16_bf16 v[66:81], v[158:161], v[162:165], v[66:81]
	ds_read_b128 v[158:161], v170 offset:0x3100
	ds_read_b128 v[162:165], v139 offset:0x1800
	s_waitcnt lgkmcnt(3)
	v_mfma_f32_32x32x16_bf16 v[82:97], v[146:149], v[166:169], v[82:97]
	ds_read_b128 v[146:149], v171 offset:0x100
	v_mfma_f32_32x32x16_bf16 v[66:81], v[150:153], v[166:169], v[66:81]
	ds_read_b128 v[150:153], v171 offset:0x3100
	ds_read_b128 v[166:169], v139 offset:0x1c00
	s_waitcnt lgkmcnt(3)
	v_mfma_f32_32x32x16_bf16 v[82:97], v[154:157], v[162:165], v[82:97]
	s_waitcnt lgkmcnt(0)
; template <int DQK, int MODE>
; DI void attn_body(const AttnArgs& a, char* lds) {
;     ...
;             float pmax = p0[0];
; #pragma unroll
;             for (int r = 1; r < 16; ++r) pmax = fmaxf(pmax, p0[r]);
; #pragma unroll
;             for (int r = 0; r < 16; ++r) pmax = fmaxf(pmax, p1[r]);
;             { auto rr = __builtin_amdgcn_permlane32_swap(__float_as_uint(pmax), __float_as_uint(pmax), false, false);
;               pmax = fmaxf(__uint_as_float(rr[0]), __uint_as_float(rr[1])); }
;             if (__builtin_expect(__all((pmax - m_reg) * C <= THR_L2), 1)) { mn = m_reg; alpha = 1.f; }
;             else { mn = fmaxf(m_reg, pmax); alpha = __builtin_amdgcn_exp2f((m_reg - mn) * C); m_reg = mn; }
;             const float mnC = -mn * C;
; #pragma unroll
;             for (int r = 0; r < 16; ++r) { p0[r] = fmaf(p0[r], C, mnC); p1[r] = fmaf(p1[r], C, mnC); }
; #pragma unroll
;             for (int r = 0; r < 16; ++r) p0[r] = __builtin_amdgcn_exp2f(p0[r]);
;         }
;     };
;     auto finishSM = [&](f32x16& p0, f32x16& p1, float alpha, bf16x8& pa0, bf16x8& pa1, bf16x8& pa2, bf16x8& pa3) {
; #pragma unroll
;         for (int r = 0; r < 16; ++r) p1[r] = __builtin_amdgcn_exp2f(p1[r]);
;         float ps = 0;
; #pragma unroll
;         for (int r = 0; r < 16; ++r) ps += p0[r];
; #pragma unroll
;         for (int r = 0; r < 16; ++r) ps += p1[r];
;         { auto rr = __builtin_amdgcn_permlane32_swap(__float_as_uint(ps), __float_as_uint(ps), false, false);
;           ps = __uint_as_float(rr[0]) + __uint_as_float(rr[1]); }
;         l_reg = l_reg * alpha + ps;
;     ...
;         PK4(p0, 0, pa0); PK4(p0, 8, pa1); PK4(p1, 0, pa2); PK4(p1, 8, pa3);
	v_mfma_f32_32x32x16_bf16 v[66:81], v[158:161], v[162:165], v[66:81]
	v_mfma_f32_32x32x16_bf16 v[82:97], v[146:149], v[166:169], v[82:97]
	v_max_f32_e32 v0, v143, v143
	v_mfma_f32_32x32x16_bf16 v[66:81], v[150:153], v[166:169], v[66:81]
	s_nop 9
	v_max_f32_e32 v145, v83, v83
	v_max_f32_e32 v146, v82, v82
	v_max_f32_e32 v145, v146, v145
	v_max3_f32 v145, v145, v84, v85
	v_max3_f32 v145, v145, v86, v87
	v_max3_f32 v145, v145, v88, v89
	v_max3_f32 v145, v145, v90, v91
	v_max3_f32 v145, v145, v92, v93
	v_max3_f32 v145, v145, v94, v95
	v_max3_f32 v145, v145, v96, v97
	v_max3_f32 v145, v145, v66, v67
	v_max3_f32 v145, v145, v68, v69
	v_max3_f32 v145, v145, v70, v71
	v_max3_f32 v145, v145, v72, v73
	v_max3_f32 v145, v145, v74, v75
	v_max3_f32 v145, v145, v76, v77
	v_max3_f32 v145, v145, v78, v79
	v_max3_f32 v145, v145, v80, v81
	v_mov_b32_e32 v146, v145
	s_nop 1
	v_permlane32_swap_b32_e32 v145, v146
	v_max_f32_e32 v146, v146, v146
	v_max_f32_e32 v145, v145, v145
	v_max_f32_e32 v145, v145, v146
	v_sub_f32_e32 v146, v145, v143
	v_max_f32_e32 v0, v0, v145
	v_mul_f32_e32 v145, 0x3dd53b94, v146
	v_sub_f32_e32 v146, v143, v0
	v_cmp_ge_f32_e32 vcc, s97, v145
	v_mul_f32_e32 v145, 0x3dd53b94, v146
	v_exp_f32_e32 v145, v145
	s_cmp_eq_u64 vcc, exec
	s_cselect_b64 vcc, -1, 0
	v_cndmask_b32_e32 v143, v0, v143, vcc
	v_cndmask_b32_e64 v0, v145, 1.0, vcc
	v_mul_f32_e32 v145, 0xbdd53b94, v143
	v_fmamk_f32 v82, v82, 0x3dd53b94, v145
	v_fmamk_f32 v66, v66, 0x3dd53b94, v145
	v_fmamk_f32 v83, v83, 0x3dd53b94, v145
	v_fmamk_f32 v67, v67, 0x3dd53b94, v145
	v_fmamk_f32 v84, v84, 0x3dd53b94, v145
	v_fmamk_f32 v68, v68, 0x3dd53b94, v145
	v_fmamk_f32 v85, v85, 0x3dd53b94, v145
	v_fmamk_f32 v69, v69, 0x3dd53b94, v145
	v_fmamk_f32 v86, v86, 0x3dd53b94, v145
	v_fmamk_f32 v70, v70, 0x3dd53b94, v145
	v_fmamk_f32 v87, v87, 0x3dd53b94, v145
	v_fmamk_f32 v71, v71, 0x3dd53b94, v145
	v_fmamk_f32 v88, v88, 0x3dd53b94, v145
	v_fmamk_f32 v72, v72, 0x3dd53b94, v145
	v_fmamk_f32 v89, v89, 0x3dd53b94, v145
	v_fmamk_f32 v73, v73, 0x3dd53b94, v145
	v_fmamk_f32 v90, v90, 0x3dd53b94, v145
	v_fmamk_f32 v74, v74, 0x3dd53b94, v145
	v_fmamk_f32 v91, v91, 0x3dd53b94, v145
	v_fmamk_f32 v75, v75, 0x3dd53b94, v145
	v_fmamk_f32 v92, v92, 0x3dd53b94, v145
	v_fmamk_f32 v76, v76, 0x3dd53b94, v145
	v_fmamk_f32 v93, v93, 0x3dd53b94, v145
	v_fmamk_f32 v77, v77, 0x3dd53b94, v145
	v_fmamk_f32 v94, v94, 0x3dd53b94, v145
	v_fmamk_f32 v78, v78, 0x3dd53b94, v145
	v_fmamk_f32 v95, v95, 0x3dd53b94, v145
	v_fmamk_f32 v79, v79, 0x3dd53b94, v145
	v_fmamk_f32 v96, v96, 0x3dd53b94, v145
	v_fmamk_f32 v80, v80, 0x3dd53b94, v145
	v_fmamk_f32 v97, v97, 0x3dd53b94, v145
	v_fmac_f32_e32 v145, 0x3dd53b94, v81
	v_exp_f32_e32 v81, v82
	v_exp_f32_e32 v146, v83
	v_exp_f32_e32 v84, v84
	v_exp_f32_e32 v85, v85
	v_exp_f32_e32 v86, v86
	v_exp_f32_e32 v147, v70
	v_add_f32_e32 v70, 0, v81
	v_exp_f32_e32 v87, v87
	v_add_f32_e32 v70, v146, v70
	v_exp_f32_e32 v88, v88
	v_add_f32_e32 v70, v84, v70
	v_exp_f32_e32 v89, v89
	v_add_f32_e32 v70, v85, v70
	v_exp_f32_e32 v90, v90
	v_add_f32_e32 v70, v86, v70
	v_exp_f32_e32 v91, v91
	v_add_f32_e32 v70, v87, v70
	v_exp_f32_e32 v92, v92
	v_add_f32_e32 v70, v88, v70
	v_exp_f32_e32 v93, v93
	v_add_f32_e32 v70, v89, v70
	v_exp_f32_e32 v94, v94
	v_add_f32_e32 v70, v90, v70
	v_exp_f32_e32 v95, v95
	v_add_f32_e32 v70, v91, v70
	v_exp_f32_e32 v96, v96
	v_add_f32_e32 v70, v92, v70
	v_exp_f32_e32 v97, v97
	v_add_f32_e32 v70, v93, v70
	v_exp_f32_e32 v66, v66
	v_add_f32_e32 v70, v94, v70
	v_exp_f32_e32 v67, v67
	v_add_f32_e32 v70, v95, v70
	v_exp_f32_e32 v68, v68
	v_add_f32_e32 v70, v96, v70
	v_exp_f32_e32 v69, v69
	v_add_f32_e32 v70, v97, v70
	v_add_f32_e32 v70, v66, v70
	v_exp_f32_e32 v148, v71
	v_add_f32_e32 v70, v67, v70
	v_exp_f32_e32 v149, v72
	v_add_f32_e32 v70, v68, v70
	v_exp_f32_e32 v73, v73
	v_add_f32_e32 v70, v69, v70
	v_exp_f32_e32 v150, v74
	v_add_f32_e32 v70, v147, v70
	v_exp_f32_e32 v151, v75
	v_add_f32_e32 v70, v148, v70
	v_exp_f32_e32 v152, v76
	v_add_f32_e32 v70, v149, v70
	v_exp_f32_e32 v153, v77
	v_add_f32_e32 v70, v73, v70
	v_exp_f32_e32 v154, v78
	v_add_f32_e32 v70, v150, v70
	v_exp_f32_e32 v155, v79
	v_add_f32_e32 v70, v151, v70
	v_exp_f32_e32 v156, v80
	v_add_f32_e32 v70, v152, v70
	v_exp_f32_e32 v145, v145
	v_add_f32_e32 v70, v153, v70
	v_add_f32_e32 v70, v154, v70
	v_add_f32_e32 v70, v155, v70
	v_add_f32_e32 v70, v156, v70
	v_add_f32_e32 v82, v145, v70
	v_mov_b32_e32 v83, v82
	v_cvt_pk_bf16_f32 v78, v81, v146
	v_cvt_pk_bf16_f32 v79, v84, v85
	v_cvt_pk_bf16_f32 v80, v86, v87
	v_cvt_pk_bf16_f32 v81, v88, v89
	v_cvt_pk_bf16_f32 v74, v90, v91
	v_cvt_pk_bf16_f32 v75, v92, v93
	v_cvt_pk_bf16_f32 v76, v94, v95
	v_cvt_pk_bf16_f32 v77, v96, v97
	v_cvt_pk_bf16_f32 v70, v66, v67
	v_cvt_pk_bf16_f32 v71, v68, v69
	v_cvt_pk_bf16_f32 v72, v147, v148
	v_cvt_pk_bf16_f32 v73, v149, v73
	v_cvt_pk_bf16_f32 v66, v150, v151
	v_cvt_pk_bf16_f32 v67, v152, v153
	v_cvt_pk_bf16_f32 v68, v154, v155
	v_cvt_pk_bf16_f32 v69, v156, v145
	s_nop 1
	v_permlane32_swap_b32_e32 v82, v83
	v_cmp_gt_f32_e32 vcc, 1.0, v0
	s_cbranch_vccz .LBB0_788
	s_and_saveexec_b64 s[10:11], s[4:5]
	ds_write_b32 v141, v0 offset:128
	s_or_b64 exec, exec, s[10:11]
	s_waitcnt lgkmcnt(0)
	v_add_u32_e32 v96, v115, v114
	ds_read_b128 v[84:87], v96 offset:224
	ds_read_b128 v[88:91], v96 offset:192
	ds_read_b128 v[92:95], v96 offset:160
	ds_read_b128 v[146:149], v96 offset:128
	s_waitcnt lgkmcnt(0)
	v_pk_mul_f32 v[62:63], v[62:63], v[84:85]
	v_pk_mul_f32 v[58:59], v[58:59], v[88:89]
	v_pk_mul_f32 v[54:55], v[54:55], v[92:93]
	v_pk_mul_f32 v[64:65], v[64:65], v[86:87]
	v_pk_mul_f32 v[60:61], v[60:61], v[90:91]
	v_pk_mul_f32 v[56:57], v[56:57], v[94:95]
	v_pk_mul_f32 v[52:53], v[52:53], v[148:149]
	v_pk_mul_f32 v[50:51], v[50:51], v[146:147]
	v_pk_mul_f32 v[46:47], v[46:47], v[84:85]
	v_pk_mul_f32 v[42:43], v[42:43], v[88:89]
	v_pk_mul_f32 v[38:39], v[38:39], v[92:93]
	v_pk_mul_f32 v[48:49], v[48:49], v[86:87]
	v_pk_mul_f32 v[44:45], v[44:45], v[90:91]
	v_pk_mul_f32 v[40:41], v[40:41], v[94:95]
	v_pk_mul_f32 v[36:37], v[36:37], v[148:149]
	v_pk_mul_f32 v[34:35], v[34:35], v[146:147]
	v_pk_mul_f32 v[30:31], v[30:31], v[84:85]
	v_pk_mul_f32 v[26:27], v[26:27], v[88:89]
	v_pk_mul_f32 v[22:23], v[22:23], v[92:93]
	v_pk_mul_f32 v[32:33], v[32:33], v[86:87]
	v_pk_mul_f32 v[28:29], v[28:29], v[90:91]
	v_pk_mul_f32 v[24:25], v[24:25], v[94:95]
	v_pk_mul_f32 v[20:21], v[20:21], v[148:149]
	v_pk_mul_f32 v[18:19], v[18:19], v[146:147]
	v_pk_mul_f32 v[14:15], v[14:15], v[84:85]
	v_pk_mul_f32 v[10:11], v[10:11], v[88:89]
	v_pk_mul_f32 v[6:7], v[6:7], v[92:93]
	v_pk_mul_f32 v[16:17], v[16:17], v[86:87]
	v_pk_mul_f32 v[12:13], v[12:13], v[90:91]
	v_pk_mul_f32 v[8:9], v[8:9], v[94:95]
	v_pk_mul_f32 v[4:5], v[4:5], v[148:149]
	v_pk_mul_f32 v[2:3], v[2:3], v[146:147]

; DI float bf2f(unsigned short b) { return __uint_as_float(((unsigned)b) << 16); }
; template <int DQK, int MODE>
; DI void attn_body(const AttnArgs& a, char* lds) {
;     ...
;     const bf16_t* Qw = a.Q + (size_t)(wid * 32 + r32) * a.ldq + hi * 8;
; #pragma unroll
;     for (int d0 = 0; d0 < NQR; ++d0) qr[d0] = *(const bf16x8*)(Qw + d0 * 16);
;     if constexpr (MODE == 2) {
;         const f32x2* rp = a.rope + (size_t)(a.qpos0 + wid * 32 + r32) * 32 + hi * 8;
; #pragma unroll
;         for (int dd = 0; dd < 2; ++dd) {
;             bf16x8 x1 = *(const bf16x8*)(Qw + (8 + dd) * 16), x2 = *(const bf16x8*)(Qw + (10 + dd) * 16); bf16x8 y1, y2;
; #pragma unroll
;             for (int j = 0; j < 8; ++j) { const f32x2 cs = rp[dd * 16 + j]; const float a1 = bf2f((unsigned short)x1[j]), a2 = bf2f((unsigned short)x2[j]);
;                 y1[j] = (short)f2bf(a1 * cs.x - a2 * cs.y); y2[j] = (short)f2bf(a1 * cs.y + a2 * cs.x); }
;             *(bf16x8*)(qrl + (8 + dd - NQR) * 1024) = y1; *(bf16x8*)(qrl + (10 + dd - NQR) * 1024) = y2; }
; #pragma unroll
;         for (int d0 = NQR; d0 < 8; ++d0) *(bf16x8*)(qrl + (d0 - NQR) * 1024) = *(const bf16x8*)(Qw + d0 * 16);
;     }
;     const int sr = tid >> 4, sc = (tid & 15) * 8, vst0 = v_st(sr, sc), vst1 = v_st(32 + sr, sc);
;     const bf16_t* vp0 = a.V + (size_t)sr * a.ldv + sc; const bf16_t* vp1 = a.V + (size_t)(32 + sr) * a.ldv + sc;
;     const bf16_t* kp[KCH]; int kld[KCH], kdst[KCH];
; #pragma unroll
;     for (int i = 0; i < KCH; ++i) { const int e = tid + i * NTHR, row = e / CPR, c = e % CPR;
;         if (MODE == 2 && c >= 16) { kp[i] = a.K2 + (size_t)row * a.ldk2 + (c - 16) * 8; kld[i] = a.ldk2; }
;         else { kp[i] = a.K + (size_t)row * a.ldk + c * 8; kld[i] = a.ldk; }
;         kdst[i] = row * KROWB + ((c * 16) ^ ksw(row)); }
;     const int vb0 = (int)(uintptr_t)V_lds + v_rd_base(lane);
;     struct { bf16x8 vs0, vs1, ks[KCH]; } st_[SD];
;     ...
;     constexpr int NI = 2 + KCH;
;     const bf16_t* sp[NI]; int sld[NI];
; #pragma unroll
;     for (int i = 0; i < NI; ++i) { const int b = wid + 8 * i;
;         if (i < 2) { const int pos = b * 1024 + lane * 16, stl = pos >> 9, q = (pos & 511) >> 1, kk = (stl >> 2) * 8 + (q >> 5), c = (stl & 3) * 32 + (q & 31);
;             const int k = (kk & ~0xC) | ((kk & 4) << 1) | ((kk & 8) >> 1);
;             sp[i] = a.V + (size_t)k * a.ldv + c; sld[i] = a.ldv;
.LBB0_802:
	s_or_b64 exec, exec, s[4:5]
	v_mov_b32_e32 v0, s88
	s_waitcnt lgkmcnt(0)
	s_barrier
	ds_read_b32 v0, v0
	s_mov_b64 s[4:5], -1
	s_waitcnt lgkmcnt(0)
	v_cmp_le_i32_e32 vcc, s12, v0
	v_readfirstlane_b32 s33, v0
	s_cbranch_vccnz .LBB0_797
	s_and_b64 vcc, exec, s[6:7]
	s_cbranch_vccz .LBB0_820
	s_lshl_b32 s4, s33, 8
	s_and_b32 s16, s4, 0x1f00
	s_and_b32 s35, s4, 0x1000
	s_or_b32 s46, s16, 0x2000
	s_bfe_u32 s17, s33, 0x30005
	s_cmpk_lt_i32 s33, 0x100
	s_cselect_b64 s[4:5], -1, 0
	s_and_b64 s[36:37], s[4:5], exec
	s_cselect_b32 s16, s46, s16
	s_mul_i32 s36, s16, 0x5c00
	s_mulk_i32 s35, 0x2e00
	s_cselect_b32 s35, 0x5c00000, s35
	s_add_u32 s36, s20, s36
	s_addc_u32 s37, s22, 0
	s_lshl_b32 s46, s17, 8
	s_add_u32 s36, s36, s46
	s_addc_u32 s37, s37, 0
	v_mov_b32_e32 v138, v193
	s_add_u32 s36, s36, 0x1800
	s_addc_u32 s37, s37, 0
	v_ashrrev_i32_e32 v141, 6, v138
	v_and_b32_e32 v143, 31, v138
	v_lshlrev_b32_e32 v140, 5, v141
	s_lshl_b32 s35, s35, 1
	v_bfe_u32 v142, v138, 5, 1
	v_or_b32_e32 v0, v140, v143
	v_mov_b64_e32 v[2:3], s[36:37]
	s_add_u32 s35, s20, s35
	v_and_b32_e32 v139, 63, v138
	v_mad_i64_i32 v[2:3], s[36:37], v0, s92, v[2:3]
	v_lshlrev_b32_e32 v0, 4, v142
	s_addc_u32 s46, s22, 0
	s_and_b32 s47, s33, 0x80
	v_lshl_add_u64 v[2:3], v[2:3], 0, v[0:1]
	v_lshlrev_b32_e32 v4, 3, v139
	s_lshl_b32 s47, s47, 1
	s_barrier
	global_load_dwordx4 v[98:101], v[2:3], off
	global_load_dwordx4 v[102:105], v[2:3], off offset:32
	global_load_dwordx4 v[106:109], v[2:3], off offset:64
	global_load_dwordx4 v[110:113], v[2:3], off offset:96
	global_load_dwordx4 v[114:117], v[2:3], off offset:128
	global_load_dwordx4 v[118:121], v[2:3], off offset:160
	global_load_dwordx4 v[122:125], v[2:3], off offset:192
	global_load_dwordx4 v[126:129], v[2:3], off offset:224
	v_and_b32_e32 v2, 24, v4
	s_add_u32 s52, s35, s47
	s_mov_b32 s89, s52
	v_bfe_u32 v6, v138, 2, 2
	v_and_or_b32 v7, v138, s13, v2
	v_lshrrev_b32_e32 v5, 1, v138
	v_lshlrev_b32_e32 v9, 2, v141
	v_lshlrev_b32_e32 v10, 2, v141
	s_addc_u32 s53, s46, 0
	s_mov_b32 s90, s53
	v_bfe_u32 v8, v138, 2, 3
	v_lshlrev_b32_e32 v6, 1, v7
	v_mov_b32_e32 v7, v1
	v_and_b32_e32 v9, -16, v9
	v_and_b32_e32 v10, 8, v10
	v_lshl_add_u64 v[6:7], s[52:53], 0, v[6:7]
	s_mov_b64 s[36:37], 0x2200
	v_or3_b32 v11, v8, v10, v9
	v_or3_b32 v8, v9, v10, v8
	v_lshl_add_u64 v[6:7], v[6:7], 0, s[36:37]
	v_add_u32_e32 v8, 32, v8
	v_lshlrev_b32_e32 v3, 4, v139
	v_mad_i64_i32 v[130:131], s[36:37], v11, s92, v[6:7]
	v_mad_i64_i32 v[132:133], s[36:37], v8, s92, v[6:7]
	v_lshlrev_b32_e32 v6, 10, v141
	v_or_b32_e32 v10, v6, v3
	v_bfe_i32 v6, v141, 21, 1
	v_add_u32_sdwa v6, v10, v6 dst_sel:DWORD dst_unused:UNUSED_PAD src0_sel:DWORD src1_sel:BYTE_3
	v_ashrrev_i32_e32 v8, 8, v6
	v_and_b32_e32 v7, 7, v8
	v_lshrrev_b32_e32 v9, 1, v8
	v_and_b32_e32 v6, 0xffffff00, v6
	v_and_or_b32 v7, v9, 8, v7
	v_sub_u32_e32 v6, v10, v6
	v_lshlrev_b32_e32 v7, 4, v7
	s_add_u32 s54, s52, 0x2000
	v_xor_b32_e32 v9, v7, v6
	s_addc_u32 s55, s53, 0
	v_mul_hi_i32_i24_e32 v7, 0x5c00, v8
	v_mul_i32_i24_e32 v6, 0x5c00, v8
	v_ashrrev_i32_e32 v8, 1, v9
	v_lshl_add_u64 v[6:7], s[54:55], 0, v[6:7]
	v_ashrrev_i32_e32 v9, 31, v8
	v_lshl_add_u64 v[134:135], v[8:9], 1, v[6:7]
	v_add_u32_e32 v6, 0x2000, v10
	v_ashrrev_i32_e32 v7, 31, v6
	v_add_u32_sdwa v7, v6, v7 dst_sel:DWORD dst_unused:UNUSED_PAD src0_sel:DWORD src1_sel:BYTE_3
	v_ashrrev_i32_e32 v8, 8, v7
	v_and_b32_e32 v7, 0xffffff00, v7
	v_sub_u32_e32 v6, v6, v7
	v_and_b32_e32 v7, 7, v8
	v_lshrrev_b32_e32 v9, 1, v8
	v_readfirstlane_b32 s35, v141
	v_and_or_b32 v7, v9, 8, v7
	s_lshl_b32 s35, s35, 10
	v_lshlrev_b32_e32 v7, 4, v7
	s_add_i32 s35, s35, 0
	v_xor_b32_e32 v9, v7, v6
	s_mov_b32 m0, s35
	v_mul_hi_i32_i24_e32 v7, 0x5c00, v8
	v_mul_i32_i24_e32 v6, 0x5c00, v8
	v_ashrrev_i32_e32 v8, 1, v9
	s_add_i32 s36, s35, 0x8000
	global_load_lds_dwordx4 v[130:131], off
	s_add_i32 m0, s35, 0x2000
	v_lshl_add_u64 v[6:7], s[54:55], 0, v[6:7]
	v_ashrrev_i32_e32 v9, 31, v8
	global_load_lds_dwordx4 v[132:133], off
	s_mov_b32 m0, s36
	v_lshl_add_u64 v[136:137], v[8:9], 1, v[6:7]
	global_load_lds_dwordx4 v[134:135], off
	s_add_i32 m0, s35, 0xa000
	v_cmp_lt_i32_e32 vcc, 3, v141
	global_load_lds_dwordx4 v[136:137], off
	s_waitcnt vmcnt(0)
	s_waitcnt vmcnt(0) lgkmcnt(0)
	s_barrier
	s_and_saveexec_b64 s[52:53], vcc
	s_cbranch_execz .Lprio_skip_3
	s_setprio 1
.Lprio_skip_3:
	s_or_b64 exec, exec, s[52:53]
	v_subrev_u32_e32 v216, s89, v130
	v_subrev_u32_e32 v217, s89, v132
	v_subrev_u32_e32 v218, s89, v134
	v_subrev_u32_e32 v219, s89, v136
	s_add_u32 s89, s89, 0x170000
	s_addc_u32 s90, s90, 0
	s_cmp_lt_u32 s35, 0x1000
	s_cbranch_scc0 .Lstg_b_pro
	s_barrier
; #define DMA(buf, k0) do { _Pragma("unroll") for (int _i = 0; _i < NI; ++_i) { \
;         char* _d = (_i < 2) ? V_lds + (buf) * SHM_V + (wu + 8 * _i) * 1024 : K_lds + (buf) * SHM_K + (wu + 8 * _i - 16) * 1024; \
;         __builtin_amdgcn_global_load_lds((const unsigned*)(sp[_i] + (size_t)(k0) * sld[_i]), (LAS unsigned*)_d, 16, 0, 0); } } while (0)
; template <int DQK, int MODE>
; DI void attn_body(const AttnArgs& a, char* lds) {
;     ...
;     constexpr int NB = (KROWB == 256) ? 8 : 4;
;     int kb[NB];
;     { const int X = (hi * 16) ^ ksw(r32);
; #pragma unroll
;       for (int i = 0; i < NB; ++i) kb[i] = (int)(uintptr_t)K_lds + r32 * KROWB + ((i * 32) ^ X); }
;     const int qra = (int)(uintptr_t)qrl;
;     ...
; #pragma unroll 1
;     for (int j = 0; j < NT; ++j) {
;         const int cur = j & 1;
;         if (j + 1 < NT) DMA(cur ^ 1, (j + 1) * 64);
;         f32x16 p0, p1; float mn, alpha;
;         qkt(p0, p1, cur * SHM_K);
.Lstg_b_pro:
	s_lshl_b32 s17, s17, 7
	s_add_i32 s36, 0, 0x14000
	s_add_i32 s37, 0, 0x8000
	s_cmp_lg_u32 s37, -1
	v_and_b32_e32 v6, 0x3fffffc0, v138
	v_and_b32_e32 v7, 7, v138
	v_and_b32_e32 v5, 8, v5
	s_cselect_b32 s37, s37, 0
	s_and_b64 s[4:5], s[4:5], exec
	v_lshl_add_u32 v144, v6, 2, s36
	v_lshlrev_b32_e32 v6, 1, v139
	v_and_b32_e32 v4, 0x100, v4
	v_bitop3_b32 v5, v5, v142, v7 bitop3:0x36
	v_and_b32_e32 v3, 0xc0, v3
	s_cselect_b32 s47, 0x80, 64
	s_cmp_lg_u32 0, -1
	v_and_b32_e32 v6, 32, v6
	v_lshlrev_b32_e32 v5, 4, v5
	v_lshl_add_u32 v7, v143, 8, s37
	v_or3_b32 v2, v3, v4, v2
	s_cselect_b32 s46, 0, 0
	v_mov_b32_e32 v16, v1
	v_mov_b32_e32 v17, v1
	v_add_u32_e32 v145, v5, v7
	v_xad_u32 v146, v5, 32, v7
	v_xad_u32 v147, v5, 64, v7
	v_xad_u32 v148, v5, s13, v7
	v_xad_u32 v150, v5, s31, v7
	v_xad_u32 v151, v5, s83, v7
	v_xad_u32 v152, v5, s73, v7
	v_xad_u32 v153, v5, s58, v7
	v_add3_u32 v154, v6, s46, v2
	v_mov_b32_e32 v2, v1
	v_mov_b32_e32 v3, v1
	v_mov_b32_e32 v4, v1
	v_mov_b32_e32 v5, v1
	v_mov_b32_e32 v6, v1
	v_mov_b32_e32 v7, v1
	v_mov_b32_e32 v8, v1
	v_mov_b32_e32 v9, v1
	v_mov_b32_e32 v10, v1
	v_mov_b32_e32 v11, v1
	v_mov_b32_e32 v12, v1
	v_mov_b32_e32 v13, v1
	v_mov_b32_e32 v14, v1
	v_mov_b32_e32 v15, v1
	v_mov_b64_e32 v[64:65], v[16:17]
	v_mov_b64_e32 v[48:49], v[16:17]
	v_mov_b64_e32 v[32:33], v[16:17]
	s_mov_b32 s36, 0
	s_mov_b32 s37, 64
	v_cmp_gt_u32_e64 s[4:5], 32, v139
	v_lshl_add_u32 v149, v143, 2, v144
	v_mov_b32_e32 v155, 0xf149f2ca
	v_mov_b32_e32 v156, 0
	v_mov_b64_e32 v[62:63], v[14:15]
	v_mov_b64_e32 v[60:61], v[12:13]
	v_mov_b64_e32 v[58:59], v[10:11]
	v_mov_b64_e32 v[56:57], v[8:9]
	v_mov_b64_e32 v[54:55], v[6:7]
	v_mov_b64_e32 v[52:53], v[4:5]
	v_mov_b64_e32 v[50:51], v[2:3]
	v_mov_b64_e32 v[46:47], v[14:15]
	v_mov_b64_e32 v[44:45], v[12:13]
	v_mov_b64_e32 v[42:43], v[10:11]
	v_mov_b64_e32 v[40:41], v[8:9]
	v_mov_b64_e32 v[38:39], v[6:7]
	v_mov_b64_e32 v[36:37], v[4:5]
	v_mov_b64_e32 v[34:35], v[2:3]
	v_mov_b64_e32 v[30:31], v[14:15]
	v_mov_b64_e32 v[28:29], v[12:13]
	v_mov_b64_e32 v[26:27], v[10:11]
	v_mov_b64_e32 v[24:25], v[8:9]
	v_mov_b64_e32 v[22:23], v[6:7]
	v_mov_b64_e32 v[20:21], v[4:5]
	v_mov_b64_e32 v[18:19], v[2:3]
.LBB0_807:
	s_and_b32 s54, s36, 1
	s_add_i32 s36, s36, 1
	s_lshl_b32 s49, s54, 14
	s_cmp_lt_u32 s36, s47
	s_cbranch_scc0 .LBB0_811
	s_xor_b32 s46, s49, 0x4000
	s_add_i32 s46, s35, s46
	s_mov_b32 s52, s89
	s_mov_b32 s53, s90
	s_add_i32 m0, s46, 0x8000
	s_nop 0
	global_load_lds_dwordx4 v218, s[52:53]
	s_add_i32 m0, s46, 0xa000
	s_nop 0
	global_load_lds_dwordx4 v219, s[52:53]
.LBB0_811:
	v_add_u32_e32 v74, s49, v145
	ds_read_b128 v[66:69], v74 offset:0
	ds_read_b128 v[70:73], v74 offset:0x2000
	v_add_u32_e32 v75, s49, v146
	ds_read_b128 v[158:161], v75 offset:0
	ds_read_b128 v[162:165], v75 offset:0x2000
	s_waitcnt lgkmcnt(2)
	v_add_u32_e32 v157, s49, v147
	v_add_u32_e32 v174, s49, v148
	v_add_u32_e32 v175, s49, v150
	v_add_u32_e32 v176, s49, v151
	v_add_u32_e32 v177, s49, v152
	v_add_u32_e32 v178, s49, v153
	v_mfma_f32_32x32x16_bf16 v[82:97], v[66:69], v[98:101], 0
	ds_read_b128 v[166:169], v157 offset:0
	ds_read_b128 v[170:173], v157 offset:0x2000
	s_waitcnt lgkmcnt(2)
	v_mfma_f32_32x32x16_bf16 v[66:81], v[70:73], v[98:101], 0
	v_mfma_f32_32x32x16_bf16 v[82:97], v[158:161], v[102:105], v[82:97]
	ds_read_b128 v[158:161], v174 offset:0
	v_mfma_f32_32x32x16_bf16 v[66:81], v[162:165], v[102:105], v[66:81]
	ds_read_b128 v[162:165], v174 offset:0x2000
	s_waitcnt lgkmcnt(2)
	v_mfma_f32_32x32x16_bf16 v[82:97], v[166:169], v[106:109], v[82:97]
	ds_read_b128 v[166:169], v175 offset:0
	v_mfma_f32_32x32x16_bf16 v[66:81], v[170:173], v[106:109], v[66:81]
	ds_read_b128 v[170:173], v175 offset:0x2000
	s_waitcnt lgkmcnt(2)
	v_mfma_f32_32x32x16_bf16 v[82:97], v[158:161], v[110:113], v[82:97]
	ds_read_b128 v[158:161], v176 offset:0
	v_mfma_f32_32x32x16_bf16 v[66:81], v[162:165], v[110:113], v[66:81]
	ds_read_b128 v[162:165], v176 offset:0x2000
	s_waitcnt lgkmcnt(2)
	v_mfma_f32_32x32x16_bf16 v[82:97], v[166:169], v[114:117], v[82:97]
	ds_read_b128 v[166:169], v177 offset:0
	v_mfma_f32_32x32x16_bf16 v[66:81], v[170:173], v[114:117], v[66:81]
	ds_read_b128 v[170:173], v177 offset:0x2000
	s_waitcnt lgkmcnt(2)
	v_mfma_f32_32x32x16_bf16 v[82:97], v[158:161], v[118:121], v[82:97]
	ds_read_b128 v[158:161], v178 offset:0
	v_mfma_f32_32x32x16_bf16 v[66:81], v[162:165], v[118:121], v[66:81]
	ds_read_b128 v[162:165], v178 offset:0x2000
	s_waitcnt lgkmcnt(2)
	v_mfma_f32_32x32x16_bf16 v[82:97], v[166:169], v[122:125], v[82:97]
	s_waitcnt lgkmcnt(0)
; template <int DQK, int MODE>
; DI void attn_body(const AttnArgs& a, char* lds) {
;     ...
;             float pmax = p0[0];
; #pragma unroll
;             for (int r = 1; r < 16; ++r) pmax = fmaxf(pmax, p0[r]);
; #pragma unroll
;             for (int r = 0; r < 16; ++r) pmax = fmaxf(pmax, p1[r]);
;             { auto rr = __builtin_amdgcn_permlane32_swap(__float_as_uint(pmax), __float_as_uint(pmax), false, false);
;               pmax = fmaxf(__uint_as_float(rr[0]), __uint_as_float(rr[1])); }
;             if (__builtin_expect(__all((pmax - m_reg) * C <= THR_L2), 1)) { mn = m_reg; alpha = 1.f; }
;             else { mn = fmaxf(m_reg, pmax); alpha = __builtin_amdgcn_exp2f((m_reg - mn) * C); m_reg = mn; }
;             const float mnC = -mn * C;
; #pragma unroll
;             for (int r = 0; r < 16; ++r) { p0[r] = fmaf(p0[r], C, mnC); p1[r] = fmaf(p1[r], C, mnC); }
; #pragma unroll
;             for (int r = 0; r < 16; ++r) p0[r] = __builtin_amdgcn_exp2f(p0[r]);
;         }
;     };
;     auto finishSM = [&](f32x16& p0, f32x16& p1, float alpha, bf16x8& pa0, bf16x8& pa1, bf16x8& pa2, bf16x8& pa3) {
; #pragma unroll
;         for (int r = 0; r < 16; ++r) p1[r] = __builtin_amdgcn_exp2f(p1[r]);
;         float ps = 0;
; #pragma unroll
;         for (int r = 0; r < 16; ++r) ps += p0[r];
; #pragma unroll
;         for (int r = 0; r < 16; ++r) ps += p1[r];
;         { auto rr = __builtin_amdgcn_permlane32_swap(__float_as_uint(ps), __float_as_uint(ps), false, false);
;           ps = __uint_as_float(rr[0]) + __uint_as_float(rr[1]); }
;         l_reg = l_reg * alpha + ps;
;     ...
;         PK4(p0, 0, pa0); PK4(p0, 8, pa1); PK4(p1, 0, pa2); PK4(p1, 8, pa3);
	v_mfma_f32_32x32x16_bf16 v[66:81], v[170:173], v[122:125], v[66:81]
	v_mfma_f32_32x32x16_bf16 v[82:97], v[158:161], v[126:129], v[82:97]
	v_max_f32_e32 v157, v155, v155
	v_mfma_f32_32x32x16_bf16 v[66:81], v[162:165], v[126:129], v[66:81]
	s_nop 9
	v_max_f32_e32 v158, v83, v83
	v_max_f32_e32 v159, v82, v82
	v_max_f32_e32 v158, v159, v158
	v_max3_f32 v158, v158, v84, v85
	v_max3_f32 v158, v158, v86, v87
	v_max3_f32 v158, v158, v88, v89
	v_max3_f32 v158, v158, v90, v91
	v_max3_f32 v158, v158, v92, v93
	v_max3_f32 v158, v158, v94, v95
	v_max3_f32 v158, v158, v96, v97
	v_max3_f32 v158, v158, v66, v67
	v_max3_f32 v158, v158, v68, v69
	v_max3_f32 v158, v158, v70, v71
	v_max3_f32 v158, v158, v72, v73
	v_max3_f32 v158, v158, v74, v75
	v_max3_f32 v158, v158, v76, v77
	v_max3_f32 v158, v158, v78, v79
	v_max3_f32 v158, v158, v80, v81
	v_mov_b32_e32 v159, v158
	s_nop 1
	v_permlane32_swap_b32_e32 v158, v159
	v_max_f32_e32 v159, v159, v159
	v_max_f32_e32 v158, v158, v158
	v_max_f32_e32 v158, v158, v159
	v_sub_f32_e32 v159, v158, v155
	v_max_f32_e32 v157, v157, v158
	v_mul_f32_e32 v158, 0x3e0293ee, v159
	v_sub_f32_e32 v159, v155, v157
	v_cmp_ge_f32_e32 vcc, s97, v158
	v_mul_f32_e32 v158, 0x3e0293ee, v159
	v_exp_f32_e32 v158, v158
	s_cmp_eq_u64 vcc, exec
	s_cselect_b64 vcc, -1, 0
	v_cndmask_b32_e32 v155, v157, v155, vcc
	v_cndmask_b32_e64 v157, v158, 1.0, vcc
	v_mul_f32_e32 v158, 0xbe0293ee, v155
	v_fmamk_f32 v82, v82, 0x3e0293ee, v158
	v_fmamk_f32 v66, v66, 0x3e0293ee, v158
	v_fmamk_f32 v83, v83, 0x3e0293ee, v158
	v_fmamk_f32 v67, v67, 0x3e0293ee, v158
	v_fmamk_f32 v84, v84, 0x3e0293ee, v158
	v_fmamk_f32 v68, v68, 0x3e0293ee, v158
	v_fmamk_f32 v85, v85, 0x3e0293ee, v158
	v_fmamk_f32 v69, v69, 0x3e0293ee, v158
	v_fmamk_f32 v86, v86, 0x3e0293ee, v158
	v_fmamk_f32 v70, v70, 0x3e0293ee, v158
	v_fmamk_f32 v87, v87, 0x3e0293ee, v158
	v_fmamk_f32 v71, v71, 0x3e0293ee, v158
	v_fmamk_f32 v88, v88, 0x3e0293ee, v158
	v_fmamk_f32 v72, v72, 0x3e0293ee, v158
	v_fmamk_f32 v89, v89, 0x3e0293ee, v158
	v_fmamk_f32 v73, v73, 0x3e0293ee, v158
	v_fmamk_f32 v90, v90, 0x3e0293ee, v158
	v_fmamk_f32 v74, v74, 0x3e0293ee, v158
	v_fmamk_f32 v91, v91, 0x3e0293ee, v158
	v_fmamk_f32 v75, v75, 0x3e0293ee, v158
	v_fmamk_f32 v92, v92, 0x3e0293ee, v158
	v_fmamk_f32 v76, v76, 0x3e0293ee, v158
	v_fmamk_f32 v93, v93, 0x3e0293ee, v158
	v_fmamk_f32 v77, v77, 0x3e0293ee, v158
	v_fmamk_f32 v94, v94, 0x3e0293ee, v158
	v_fmamk_f32 v78, v78, 0x3e0293ee, v158
	v_fmamk_f32 v95, v95, 0x3e0293ee, v158
	v_fmamk_f32 v79, v79, 0x3e0293ee, v158
	v_fmamk_f32 v96, v96, 0x3e0293ee, v158
	v_fmamk_f32 v80, v80, 0x3e0293ee, v158
	v_fmamk_f32 v97, v97, 0x3e0293ee, v158
	v_fmac_f32_e32 v158, 0x3e0293ee, v81
	s_waitcnt vmcnt(0)
	s_barrier
	s_cmp_lt_u32 s36, s47
	s_cbranch_scc0 .Lstg_b_nov
	s_xor_b32 s46, s49, 0x4000
	s_add_i32 s46, s35, s46
	s_mov_b32 s52, s89
	s_mov_b32 s53, s90
	s_mov_b32 m0, s46
	s_nop 0
	global_load_lds_dwordx4 v216, s[52:53]
	s_add_i32 m0, s46, 0x2000
	s_nop 0
	global_load_lds_dwordx4 v217, s[52:53]
.Lstg_b_nov:
	v_exp_f32_e32 v81, v82
	v_exp_f32_e32 v159, v83
	v_exp_f32_e32 v84, v84
	v_exp_f32_e32 v85, v85
	v_exp_f32_e32 v86, v86
	v_exp_f32_e32 v160, v70
	v_add_f32_e32 v70, 0, v81
	v_exp_f32_e32 v87, v87
	v_add_f32_e32 v70, v159, v70
	v_exp_f32_e32 v88, v88
	v_add_f32_e32 v70, v84, v70
	v_exp_f32_e32 v89, v89
	v_add_f32_e32 v70, v85, v70
	v_exp_f32_e32 v90, v90
	v_add_f32_e32 v70, v86, v70
	v_exp_f32_e32 v91, v91
	v_add_f32_e32 v70, v87, v70
	v_exp_f32_e32 v92, v92
	v_add_f32_e32 v70, v88, v70
	v_exp_f32_e32 v93, v93
	v_add_f32_e32 v70, v89, v70
	v_exp_f32_e32 v94, v94
	v_add_f32_e32 v70, v90, v70
	v_exp_f32_e32 v95, v95
	v_add_f32_e32 v70, v91, v70
	v_exp_f32_e32 v96, v96
	v_add_f32_e32 v70, v92, v70
	v_exp_f32_e32 v97, v97
	v_add_f32_e32 v70, v93, v70
	v_exp_f32_e32 v66, v66
	v_add_f32_e32 v70, v94, v70
	v_exp_f32_e32 v67, v67
	v_add_f32_e32 v70, v95, v70
	v_exp_f32_e32 v68, v68
	v_add_f32_e32 v70, v96, v70
	v_exp_f32_e32 v69, v69
	v_add_f32_e32 v70, v97, v70
	v_add_f32_e32 v70, v66, v70
	v_exp_f32_e32 v161, v71
	v_add_f32_e32 v70, v67, v70
	v_exp_f32_e32 v162, v72
	v_add_f32_e32 v70, v68, v70
	v_exp_f32_e32 v73, v73
	v_add_f32_e32 v70, v69, v70
	v_exp_f32_e32 v163, v74
	v_add_f32_e32 v70, v160, v70
	v_exp_f32_e32 v164, v75
	v_add_f32_e32 v70, v161, v70
	v_exp_f32_e32 v165, v76
	v_add_f32_e32 v70, v162, v70
	v_exp_f32_e32 v166, v77
	v_add_f32_e32 v70, v73, v70
	v_exp_f32_e32 v167, v78
	v_add_f32_e32 v70, v163, v70
	v_exp_f32_e32 v168, v79
	v_add_f32_e32 v70, v164, v70
	v_exp_f32_e32 v169, v80
	v_add_f32_e32 v70, v165, v70
	v_exp_f32_e32 v158, v158
	v_add_f32_e32 v70, v166, v70
	v_add_f32_e32 v70, v167, v70
	v_add_f32_e32 v70, v168, v70
	v_add_f32_e32 v70, v169, v70
	v_add_f32_e32 v82, v158, v70
	v_mov_b32_e32 v83, v82
	v_cvt_pk_bf16_f32 v78, v81, v159
	v_cvt_pk_bf16_f32 v79, v84, v85
	v_cvt_pk_bf16_f32 v80, v86, v87
	v_cvt_pk_bf16_f32 v81, v88, v89
	v_cvt_pk_bf16_f32 v74, v90, v91
	v_cvt_pk_bf16_f32 v75, v92, v93
	v_cvt_pk_bf16_f32 v76, v94, v95
	v_cvt_pk_bf16_f32 v77, v96, v97
	v_cvt_pk_bf16_f32 v70, v66, v67
	v_cvt_pk_bf16_f32 v71, v68, v69
	v_cvt_pk_bf16_f32 v72, v160, v161
	v_cvt_pk_bf16_f32 v73, v162, v73
	v_cvt_pk_bf16_f32 v66, v163, v164
	v_cvt_pk_bf16_f32 v67, v165, v166
	v_cvt_pk_bf16_f32 v68, v167, v168
	v_cvt_pk_bf16_f32 v69, v169, v158
	s_nop 1
	v_permlane32_swap_b32_e32 v82, v83
	v_cmp_gt_f32_e32 vcc, 1.0, v157
	s_cbranch_vccz .LBB0_815
; #define SBAR() __builtin_amdgcn_sched_barrier(0)
; template <int N> DI void wait_lgkm() { asm volatile("s_waitcnt lgkmcnt(%0)" :: "i"(N) : "memory"); }
; #define RESC(al) do { if (__any((al) < 1.f)) { if (hi == 0) al_l[r32] = (al); asm volatile("s_waitcnt lgkmcnt(0)" ::: "memory"); \
;     _Pragma("unroll") for (int d = 0; d < 4; ++d) _Pragma("unroll") for (int r = 0; r < 16; ++r) o[d][r] *= al_l[crow(r, hi)]; } } while (0)
; DI void pv_d0(f32x16* o, int vb, bf16x8 pa0, bf16x8 pa1, bf16x8 pa2, bf16x8 pa3) {
;     s16x4 fa[8], fb[8];
;     v_rd8<0>(fa, vb);
;     v_rd8<1>(fb, vb); wait_lgkm<8>(); SBAR(); pv_mm(o, fa, pa0);
;     v_rd8<2>(fa, vb); wait_lgkm<8>(); SBAR(); pv_mm(o, fb, pa1);
;     v_rd8<3>(fb, vb); wait_lgkm<8>(); SBAR(); pv_mm(o, fa, pa2);
;     wait_lgkm<0>(); SBAR(); pv_mm(o, fb, pa3);
; }
; template <int DQK, int MODE>
; DI void attn_body(const AttnArgs& a, char* lds) {
;     ...
;         RESC(alpha);
;         pv_d0(o, vb0 + cur * SHM_V, pa0, pa1, pa2, pa3);
;         asm volatile("s_waitcnt vmcnt(0)" ::: "memory");
;         __syncthreads();
;     }
;     __builtin_amdgcn_s_setprio(0);
	s_and_saveexec_b64 s[52:53], s[4:5]
	ds_write_b32 v149, v157 offset:128
	s_or_b64 exec, exec, s[52:53]
	s_waitcnt lgkmcnt(0)
	v_add_u32_e32 v96, v144, v0
	ds_read_b128 v[84:87], v96 offset:224
	ds_read_b128 v[88:91], v96 offset:192
	ds_read_b128 v[92:95], v96 offset:160
	ds_read_b128 v[158:161], v96 offset:128
	s_waitcnt lgkmcnt(0)
	v_pk_mul_f32 v[14:15], v[14:15], v[84:85]
	v_pk_mul_f32 v[10:11], v[10:11], v[88:89]
	v_pk_mul_f32 v[6:7], v[6:7], v[92:93]
	v_pk_mul_f32 v[16:17], v[16:17], v[86:87]
	v_pk_mul_f32 v[12:13], v[12:13], v[90:91]
	v_pk_mul_f32 v[8:9], v[8:9], v[94:95]
	v_pk_mul_f32 v[4:5], v[4:5], v[160:161]
	v_pk_mul_f32 v[2:3], v[2:3], v[158:159]
	v_pk_mul_f32 v[62:63], v[62:63], v[84:85]
	v_pk_mul_f32 v[58:59], v[58:59], v[88:89]
	v_pk_mul_f32 v[54:55], v[54:55], v[92:93]
	v_pk_mul_f32 v[64:65], v[64:65], v[86:87]
	v_pk_mul_f32 v[60:61], v[60:61], v[90:91]
	v_pk_mul_f32 v[56:57], v[56:57], v[94:95]
	v_pk_mul_f32 v[52:53], v[52:53], v[160:161]
	v_pk_mul_f32 v[50:51], v[50:51], v[158:159]
	v_pk_mul_f32 v[46:47], v[46:47], v[84:85]
	v_pk_mul_f32 v[42:43], v[42:43], v[88:89]
	v_pk_mul_f32 v[38:39], v[38:39], v[92:93]
	v_pk_mul_f32 v[48:49], v[48:49], v[86:87]
	v_pk_mul_f32 v[44:45], v[44:45], v[90:91]
	v_pk_mul_f32 v[40:41], v[40:41], v[94:95]
	v_pk_mul_f32 v[36:37], v[36:37], v[160:161]
	v_pk_mul_f32 v[34:35], v[34:35], v[158:159]
	v_pk_mul_f32 v[30:31], v[30:31], v[84:85]
	v_pk_mul_f32 v[26:27], v[26:27], v[88:89]
	v_pk_mul_f32 v[22:23], v[22:23], v[92:93]
	v_pk_mul_f32 v[32:33], v[32:33], v[86:87]
	v_pk_mul_f32 v[28:29], v[28:29], v[90:91]
	v_pk_mul_f32 v[24:25], v[24:25], v[94:95]
	v_pk_mul_f32 v[20:21], v[20:21], v[160:161]
	v_pk_mul_f32 v[18:19], v[18:19], v[158:159]
.LBB0_815:
	v_add_f32_e32 v82, v82, v83
	v_add_u32_e32 v83, s49, v154
	ds_read_b64_tr_b16 v[84:85], v83 offset:0
	ds_read_b64_tr_b16 v[86:87], v83 offset:0x800
	ds_read_b64_tr_b16 v[88:89], v83 offset:0x200
	ds_read_b64_tr_b16 v[90:91], v83 offset:0xa00
	ds_read_b64_tr_b16 v[92:93], v83 offset:0x400
	ds_read_b64_tr_b16 v[94:95], v83 offset:0xc00
	v_fmac_f32_e32 v82, v156, v157
	ds_read_b64_tr_b16 v[156:157], v83 offset:0x600
	ds_read_b64_tr_b16 v[158:159], v83 offset:0xe00
	ds_read_b64_tr_b16 v[160:161], v83 offset:0x1000
	ds_read_b64_tr_b16 v[162:163], v83 offset:0x1800
	ds_read_b64_tr_b16 v[164:165], v83 offset:0x1200
	ds_read_b64_tr_b16 v[166:167], v83 offset:0x1a00
	ds_read_b64_tr_b16 v[168:169], v83 offset:0x1400
	ds_read_b64_tr_b16 v[170:171], v83 offset:0x1c00
	ds_read_b64_tr_b16 v[172:173], v83 offset:0x1600
	ds_read_b64_tr_b16 v[174:175], v83 offset:0x1e00
	s_waitcnt lgkmcnt(8)
	v_mfma_f32_32x32x16_bf16 v[2:17], v[78:81], v[84:87], v[2:17]
	v_mfma_f32_32x32x16_bf16 v[50:65], v[78:81], v[88:91], v[50:65]
	v_mfma_f32_32x32x16_bf16 v[34:49], v[78:81], v[92:95], v[34:49]
	v_mfma_f32_32x32x16_bf16 v[18:33], v[78:81], v[156:159], v[18:33]
	ds_read_b64_tr_b16 v[78:79], v83 offset:0x2000
	ds_read_b64_tr_b16 v[80:81], v83 offset:0x2800
	ds_read_b64_tr_b16 v[84:85], v83 offset:0x2200
	ds_read_b64_tr_b16 v[86:87], v83 offset:0x2a00
	ds_read_b64_tr_b16 v[88:89], v83 offset:0x2400
	ds_read_b64_tr_b16 v[90:91], v83 offset:0x2c00
	ds_read_b64_tr_b16 v[92:93], v83 offset:0x2600
	ds_read_b64_tr_b16 v[94:95], v83 offset:0x2e00
	s_waitcnt lgkmcnt(8)
	v_mfma_f32_32x32x16_bf16 v[2:17], v[74:77], v[160:163], v[2:17]
	v_mfma_f32_32x32x16_bf16 v[50:65], v[74:77], v[164:167], v[50:65]
	v_mfma_f32_32x32x16_bf16 v[34:49], v[74:77], v[168:171], v[34:49]
	v_mfma_f32_32x32x16_bf16 v[18:33], v[74:77], v[172:175], v[18:33]
	ds_read_b64_tr_b16 v[74:75], v83 offset:0x3000
	ds_read_b64_tr_b16 v[76:77], v83 offset:0x3800
	ds_read_b64_tr_b16 v[156:157], v83 offset:0x3200
	ds_read_b64_tr_b16 v[158:159], v83 offset:0x3a00
	ds_read_b64_tr_b16 v[160:161], v83 offset:0x3400
	ds_read_b64_tr_b16 v[162:163], v83 offset:0x3c00
	ds_read_b64_tr_b16 v[164:165], v83 offset:0x3600
	ds_read_b64_tr_b16 v[166:167], v83 offset:0x3e00
	s_waitcnt lgkmcnt(8)
	v_mfma_f32_32x32x16_bf16 v[2:17], v[70:73], v[78:81], v[2:17]
	s_waitcnt lgkmcnt(0)
	v_mfma_f32_32x32x16_bf16 v[50:65], v[70:73], v[84:87], v[50:65]
	v_mfma_f32_32x32x16_bf16 v[34:49], v[70:73], v[88:91], v[34:49]
	v_mfma_f32_32x32x16_bf16 v[18:33], v[70:73], v[92:95], v[18:33]
	v_mfma_f32_32x32x16_bf16 v[2:17], v[66:69], v[74:77], v[2:17]
	s_waitcnt vmcnt(0)
	s_add_i32 s37, s37, 64
	s_add_u32 s89, s89, 0x170000
	s_addc_u32 s90, s90, 0
	s_cmp_eq_u32 s47, s36
	s_waitcnt vmcnt(0) lgkmcnt(0)
	s_barrier
	v_mfma_f32_32x32x16_bf16 v[50:65], v[66:69], v[156:159], v[50:65]
	v_mfma_f32_32x32x16_bf16 v[34:49], v[66:69], v[160:163], v[34:49]
	v_mfma_f32_32x32x16_bf16 v[18:33], v[66:69], v[164:167], v[18:33]
	s_cbranch_scc1 .LBB0_817
	v_mov_b32_e32 v156, v82
	s_branch .LBB0_807
.LBB0_817:
	s_setprio 0
	s_cmp_lt_u32 s35, 0x1000
	s_cbranch_scc1 .Lstg_b_epi
	s_barrier
; DI unsigned short f2bf(float f) { return (unsigned short)(cvtpk(f, f) & 0xffffu); }
; DI int crow(int r, int hi) { return (r & 3) + 8 * (r >> 2) + 4 * hi; }
; template <int DQK, int MODE>
; DI void attn_body(const AttnArgs& a, char* lds) {
;     ...
;     if (hi == 0) li_l[r32] = l_reg; asm volatile("s_waitcnt lgkmcnt(0)" ::: "memory");
;     char* ost = lds + wid * 8192;
; #pragma unroll
;     for (int r = 0; r < 16; ++r) { const int orow = crow(r, hi); const float rl = __builtin_amdgcn_rcpf(li_l[orow]);
; #pragma unroll
;         for (int d0 = 0; d0 < 4; ++d0) *(bf16_t*)(ost + orow * 256 + (d0 * 32 + r32) * 2) = f2bf(o[d0][r] * rl); }
.Lstg_b_epi:
	s_and_saveexec_b64 s[52:53], s[4:5]
	ds_write_b32 v149, v82
	s_or_b64 exec, exec, s[52:53]
	s_waitcnt lgkmcnt(0)
	v_add_u32_e32 v66, v144, v0
	ds_read_b32 v67, v66
	v_lshlrev_b32_e32 v0, 13, v141
	v_lshlrev_b32_e32 v68, 1, v143
	v_lshlrev_b32_e32 v69, 10, v142
	v_add_u32_e32 v70, 0, v0
	s_waitcnt lgkmcnt(0)
	v_rcp_f32_e32 v67, v67
	v_add3_u32 v68, v70, v68, v69
	s_mulk_i32 s16, 0x1800
	s_add_u32 s4, s15, s16
	v_mul_f32_e32 v2, v2, v67
	v_cvt_pk_bf16_f32 v2, v2, v2
	v_mul_f32_e32 v50, v50, v67
	ds_write_b16 v68, v2
	v_cvt_pk_bf16_f32 v2, v50, v50
	ds_write_b16 v68, v2 offset:64
	v_mul_f32_e32 v2, v34, v67
	v_cvt_pk_bf16_f32 v2, v2, v2
	ds_write_b16 v68, v2 offset:128
	v_mul_f32_e32 v2, v18, v67
	v_cvt_pk_bf16_f32 v2, v2, v2
	ds_read_b32 v18, v66 offset:4
	ds_write_b16 v68, v2 offset:192
	s_addc_u32 s5, s14, 0
	s_lshl_b32 s16, s17, 1
	s_add_u32 s4, s4, s16
	s_waitcnt lgkmcnt(1)
	v_rcp_f32_e32 v18, v18
	s_addc_u32 s5, s5, 0
	s_add_u32 s4, s4, 0x1fc80800
	s_addc_u32 s5, s5, 0
	v_mul_f32_e32 v2, v3, v18
	v_cvt_pk_bf16_f32 v2, v2, v2
	ds_write_b16 v68, v2 offset:256
	v_mul_f32_e32 v2, v51, v18
	v_cvt_pk_bf16_f32 v2, v2, v2
	ds_write_b16 v68, v2 offset:320
	v_mul_f32_e32 v2, v35, v18
	v_cvt_pk_bf16_f32 v2, v2, v2
	ds_write_b16 v68, v2 offset:384
	v_mul_f32_e32 v2, v19, v18
	v_cvt_pk_bf16_f32 v2, v2, v2
	ds_read_b32 v3, v66 offset:8
	ds_write_b16 v68, v2 offset:448
	s_waitcnt lgkmcnt(1)
	v_rcp_f32_e32 v3, v3
	s_nop 0
	v_mul_f32_e32 v2, v4, v3
	v_cvt_pk_bf16_f32 v2, v2, v2
	ds_write_b16 v68, v2 offset:512
	v_mul_f32_e32 v2, v52, v3
	v_cvt_pk_bf16_f32 v2, v2, v2
	ds_write_b16 v68, v2 offset:576
	v_mul_f32_e32 v2, v36, v3
	v_cvt_pk_bf16_f32 v2, v2, v2
	ds_write_b16 v68, v2 offset:640
	v_mul_f32_e32 v2, v20, v3
	v_cvt_pk_bf16_f32 v2, v2, v2
	ds_read_b32 v3, v66 offset:12
	ds_write_b16 v68, v2 offset:704
	v_lshrrev_b32_e32 v4, 1, v139
	s_waitcnt lgkmcnt(1)
	v_rcp_f32_e32 v3, v3
	s_nop 0
	v_mul_f32_e32 v2, v5, v3
	v_cvt_pk_bf16_f32 v2, v2, v2
	ds_write_b16 v68, v2 offset:768
	v_mul_f32_e32 v2, v53, v3
	v_cvt_pk_bf16_f32 v2, v2, v2
	ds_write_b16 v68, v2 offset:832
	v_mul_f32_e32 v2, v37, v3
	v_cvt_pk_bf16_f32 v2, v2, v2
	ds_write_b16 v68, v2 offset:896
	v_mul_f32_e32 v2, v21, v3
	v_cvt_pk_bf16_f32 v2, v2, v2
	ds_read_b32 v3, v66 offset:32
	ds_write_b16 v68, v2 offset:960
	v_or_b32_e32 v5, v140, v4
	s_waitcnt lgkmcnt(1)
	v_rcp_f32_e32 v3, v3
	s_nop 0
	v_mul_f32_e32 v2, v6, v3
	v_cvt_pk_bf16_f32 v2, v2, v2
	ds_write_b16 v68, v2 offset:2048
	v_mul_f32_e32 v2, v54, v3
	v_cvt_pk_bf16_f32 v2, v2, v2
	ds_write_b16 v68, v2 offset:2112
	v_mul_f32_e32 v2, v38, v3
	v_cvt_pk_bf16_f32 v2, v2, v2
	ds_write_b16 v68, v2 offset:2176
	v_mul_f32_e32 v2, v22, v3
	v_cvt_pk_bf16_f32 v2, v2, v2
	ds_read_b32 v3, v66 offset:36
	ds_write_b16 v68, v2 offset:2240
	s_waitcnt lgkmcnt(1)
	v_rcp_f32_e32 v3, v3
	s_nop 0
	v_mul_f32_e32 v2, v7, v3
	v_cvt_pk_bf16_f32 v2, v2, v2
	ds_write_b16 v68, v2 offset:2304
	v_mul_f32_e32 v2, v55, v3
	v_cvt_pk_bf16_f32 v2, v2, v2
	ds_write_b16 v68, v2 offset:2368
	v_mul_f32_e32 v2, v39, v3
	v_cvt_pk_bf16_f32 v2, v2, v2
	ds_write_b16 v68, v2 offset:2432
	v_mul_f32_e32 v2, v23, v3
	v_cvt_pk_bf16_f32 v2, v2, v2
	ds_read_b32 v3, v66 offset:40
	ds_write_b16 v68, v2 offset:2496
	s_waitcnt lgkmcnt(1)
	v_rcp_f32_e32 v3, v3
	s_nop 0
	v_mul_f32_e32 v2, v8, v3
	v_cvt_pk_bf16_f32 v2, v2, v2
	ds_write_b16 v68, v2 offset:2560
	v_mul_f32_e32 v2, v56, v3
	v_cvt_pk_bf16_f32 v2, v2, v2
	ds_write_b16 v68, v2 offset:2624
	v_mul_f32_e32 v2, v40, v3
	v_cvt_pk_bf16_f32 v2, v2, v2
	ds_write_b16 v68, v2 offset:2688
	v_mul_f32_e32 v2, v24, v3
	v_cvt_pk_bf16_f32 v2, v2, v2
	ds_read_b32 v3, v66 offset:44
	ds_write_b16 v68, v2 offset:2752
	s_waitcnt lgkmcnt(1)
	v_rcp_f32_e32 v3, v3
	s_nop 0
	v_mul_f32_e32 v2, v9, v3
	v_cvt_pk_bf16_f32 v2, v2, v2
	ds_write_b16 v68, v2 offset:2816
	v_mul_f32_e32 v2, v57, v3
	v_cvt_pk_bf16_f32 v2, v2, v2
	ds_write_b16 v68, v2 offset:2880
	v_mul_f32_e32 v2, v41, v3
	v_cvt_pk_bf16_f32 v2, v2, v2
	ds_write_b16 v68, v2 offset:2944
	v_mul_f32_e32 v2, v25, v3
	v_cvt_pk_bf16_f32 v2, v2, v2
	ds_read_b32 v3, v66 offset:64
	ds_write_b16 v68, v2 offset:3008
	s_waitcnt lgkmcnt(1)
	v_rcp_f32_e32 v3, v3
	s_nop 0
	v_mul_f32_e32 v2, v10, v3
	v_cvt_pk_bf16_f32 v2, v2, v2
	ds_write_b16 v68, v2 offset:4096
	v_mul_f32_e32 v2, v58, v3
	v_cvt_pk_bf16_f32 v2, v2, v2
	ds_write_b16 v68, v2 offset:4160
	v_mul_f32_e32 v2, v42, v3
	v_cvt_pk_bf16_f32 v2, v2, v2
	ds_write_b16 v68, v2 offset:4224
	v_mul_f32_e32 v2, v26, v3
	v_cvt_pk_bf16_f32 v2, v2, v2
	ds_read_b32 v3, v66 offset:68
	ds_write_b16 v68, v2 offset:4288
	s_waitcnt lgkmcnt(1)
	v_rcp_f32_e32 v3, v3
	s_nop 0
	v_mul_f32_e32 v2, v11, v3
	v_cvt_pk_bf16_f32 v2, v2, v2
	ds_write_b16 v68, v2 offset:4352
	v_mul_f32_e32 v2, v59, v3
	v_cvt_pk_bf16_f32 v2, v2, v2
	ds_write_b16 v68, v2 offset:4416
	v_mul_f32_e32 v2, v43, v3
	v_cvt_pk_bf16_f32 v2, v2, v2
	ds_write_b16 v68, v2 offset:4480
	v_mul_f32_e32 v2, v27, v3
	v_cvt_pk_bf16_f32 v2, v2, v2
	ds_read_b32 v3, v66 offset:72
	ds_write_b16 v68, v2 offset:4544
	s_waitcnt lgkmcnt(1)
	v_rcp_f32_e32 v3, v3
	s_nop 0
	v_mul_f32_e32 v2, v12, v3
	v_cvt_pk_bf16_f32 v2, v2, v2
	ds_write_b16 v68, v2 offset:4608
	v_mul_f32_e32 v2, v60, v3
	v_cvt_pk_bf16_f32 v2, v2, v2
	ds_write_b16 v68, v2 offset:4672
	v_mul_f32_e32 v2, v44, v3
	v_cvt_pk_bf16_f32 v2, v2, v2
	ds_write_b16 v68, v2 offset:4736
	v_mul_f32_e32 v2, v28, v3
	v_cvt_pk_bf16_f32 v2, v2, v2
	ds_read_b32 v3, v66 offset:76
	ds_write_b16 v68, v2 offset:4800
	s_waitcnt lgkmcnt(1)
;     DI void* gp(int i) const { return (void*)(__attribute__((address_space(1))) void*)ld(i); }
;     DI unsigned char* ws() const { return (unsigned char*)gp(35); }
; DI unsigned short f2bf(float f) { return (unsigned short)(cvtpk(f, f) & 0xffffu); }
; DI int crow(int r, int hi) { return (r & 3) + 8 * (r >> 2) + 4 * hi; }
; template <int DQK, int MODE>
; DI void attn_body(const AttnArgs& a, char* lds) {
;     ...
;     if (hi == 0) li_l[r32] = l_reg; asm volatile("s_waitcnt lgkmcnt(0)" ::: "memory");
;     char* ost = lds + wid * 8192;
; #pragma unroll
;     for (int r = 0; r < 16; ++r) { const int orow = crow(r, hi); const float rl = __builtin_amdgcn_rcpf(li_l[orow]);
; #pragma unroll
;         for (int d0 = 0; d0 < 4; ++d0) *(bf16_t*)(ost + orow * 256 + (d0 * 32 + r32) * 2) = f2bf(o[d0][r] * rl); }
;     asm volatile("s_waitcnt lgkmcnt(0)" ::: "memory");
;     {
;         const int row = lane >> 1, hf = lane & 1;
;         bf16_t* gp = a.O + (size_t)(wid * 32 + row) * a.ldo + hf * 64;
; template <int TYPE>
; DI void attn_phase(const Params& P, int l, unsigned char* shm, const int rep, const bool cross = false) {
;     ...
;             const bf16_t* xq = (const bf16_t*)(ws + WS_XQ); const bf16_t* mkv = (const bf16_t*)(ws + WS_MEMKV); bf16_t* xatt = (bf16_t*)(ws + WS_XATT);
;             const int xh = idx >> 6, qb = idx & 63, xt0 = qb * 256, sq = qb < 16 ? 0 : (qb < 32 ? 1 : 2);
;             a.qpos0 = 0; a.seq = 256;
;             a.Q = xq + (size_t)xt0 * 512 + xh * 128; a.ldq = 512; a.K = mkv + (size_t)sq * 256 * 1024 + xh * 128; a.ldk = 1024;
;             a.V = mkv + (size_t)sq * 256 * 1024 + 512 + xh * 128; a.ldv = 1024; a.O = xatt + (size_t)xt0 * 512 + xh * 128; a.ldo = 512; a.C = 0.08838834764831845f * LOG2E;
;             attn_body<128, 0>(a, (char*)shm);
	v_rcp_f32_e32 v3, v3
	s_nop 0
	v_mul_f32_e32 v2, v13, v3
	v_cvt_pk_bf16_f32 v2, v2, v2
	ds_write_b16 v68, v2 offset:4864
	v_mul_f32_e32 v2, v61, v3
	v_cvt_pk_bf16_f32 v2, v2, v2
	ds_write_b16 v68, v2 offset:4928
	v_mul_f32_e32 v2, v45, v3
	v_cvt_pk_bf16_f32 v2, v2, v2
	ds_write_b16 v68, v2 offset:4992
	v_mul_f32_e32 v2, v29, v3
	v_cvt_pk_bf16_f32 v2, v2, v2
	ds_read_b32 v3, v66 offset:96
	ds_write_b16 v68, v2 offset:5056
	s_waitcnt lgkmcnt(1)
	v_rcp_f32_e32 v3, v3
	s_nop 0
	v_mul_f32_e32 v2, v14, v3
	v_cvt_pk_bf16_f32 v2, v2, v2
	ds_write_b16 v68, v2 offset:6144
	v_mul_f32_e32 v2, v62, v3
	v_cvt_pk_bf16_f32 v2, v2, v2
	ds_write_b16 v68, v2 offset:6208
	v_mul_f32_e32 v2, v46, v3
	v_cvt_pk_bf16_f32 v2, v2, v2
	ds_write_b16 v68, v2 offset:6272
	v_mul_f32_e32 v2, v30, v3
	v_cvt_pk_bf16_f32 v2, v2, v2
	ds_read_b32 v3, v66 offset:100
	ds_write_b16 v68, v2 offset:6336
	s_waitcnt lgkmcnt(1)
	v_rcp_f32_e32 v3, v3
	s_nop 0
	v_mul_f32_e32 v2, v15, v3
	v_cvt_pk_bf16_f32 v2, v2, v2
	ds_write_b16 v68, v2 offset:6400
	v_mul_f32_e32 v2, v63, v3
	v_cvt_pk_bf16_f32 v2, v2, v2
	ds_write_b16 v68, v2 offset:6464
	v_mul_f32_e32 v2, v47, v3
	v_cvt_pk_bf16_f32 v2, v2, v2
	ds_write_b16 v68, v2 offset:6528
	v_mul_f32_e32 v2, v31, v3
	v_cvt_pk_bf16_f32 v2, v2, v2
	ds_read_b32 v3, v66 offset:104
	ds_write_b16 v68, v2 offset:6592
	s_waitcnt lgkmcnt(1)
	v_rcp_f32_e32 v3, v3
	s_nop 0
	v_mul_f32_e32 v2, v16, v3
	v_cvt_pk_bf16_f32 v2, v2, v2
	ds_write_b16 v68, v2 offset:6656
	v_mul_f32_e32 v2, v64, v3
	v_cvt_pk_bf16_f32 v2, v2, v2
	ds_write_b16 v68, v2 offset:6720
	v_mul_f32_e32 v2, v48, v3
	v_cvt_pk_bf16_f32 v2, v2, v2
	ds_write_b16 v68, v2 offset:6784
	v_mul_f32_e32 v2, v32, v3
	v_cvt_pk_bf16_f32 v2, v2, v2
	ds_read_b32 v3, v66 offset:108
	ds_write_b16 v68, v2 offset:6848
	s_waitcnt lgkmcnt(1)
	v_rcp_f32_e32 v3, v3
	s_nop 0
	v_mul_f32_e32 v2, v17, v3
	v_cvt_pk_bf16_f32 v2, v2, v2
	ds_write_b16 v68, v2 offset:6912
	v_mul_f32_e32 v2, v65, v3
	v_cvt_pk_bf16_f32 v2, v2, v2
	ds_write_b16 v68, v2 offset:6976
	v_mul_f32_e32 v2, v49, v3
	v_cvt_pk_bf16_f32 v2, v2, v2
	ds_write_b16 v68, v2 offset:7040
	v_mul_f32_e32 v2, v33, v3
	v_cvt_pk_bf16_f32 v2, v2, v2
	ds_write_b16 v68, v2 offset:7104
	s_waitcnt lgkmcnt(0)
	v_mov_b64_e32 v[2:3], s[4:5]
	v_mad_i64_i32 v[2:3], s[4:5], v5, s23, v[2:3]
	s_mov_b64 s[4:5], 0
.LBB0_820:
	s_and_b64 vcc, exec, s[4:5]
	s_cbranch_vccz .LBB0_796
	s_and_b32 s16, s33, 63
	s_cmp_lt_u32 s16, 32
	s_mov_b32 s4, 0x80000
	s_cselect_b32 s4, 0x40000, s4
	s_cmp_gt_u32 s16, 15
	s_cselect_b32 s17, s4, 0
	s_lshl_b32 s4, s16, 18
	s_add_u32 s35, s20, s4
	s_addc_u32 s37, s22, 0
	s_lshl_b32 s4, s33, 1
	v_mov_b32_e32 v138, v193
	s_and_b32 s4, s4, 0xffffff80
	s_ashr_i32 s5, s4, 31
	v_ashrrev_i32_e32 v141, 6, v138
	v_and_b32_e32 v143, 31, v138
	v_lshlrev_b32_e32 v140, 5, v141
	s_lshl_b64 s[52:53], s[4:5], 1
	v_or_b32_e32 v2, v140, v143
	s_add_u32 s36, s35, s52
	v_ashrrev_i32_e32 v3, 31, v2
	s_addc_u32 s37, s37, s53
	v_bfe_u32 v142, v138, 5, 1
	v_lshlrev_b64 v[2:3], 10, v[2:3]
	v_lshl_add_u64 v[2:3], s[36:37], 0, v[2:3]
	v_lshlrev_b32_e32 v0, 4, v142
	v_lshl_add_u64 v[2:3], v[2:3], 0, v[0:1]
	s_lshl_b32 s35, s17, 1
	v_and_b32_e32 v139, 63, v138
	s_waitcnt lgkmcnt(0)
	s_barrier
	global_load_dwordx4 v[98:101], v[2:3], off
	global_load_dwordx4 v[102:105], v[2:3], off offset:32
	global_load_dwordx4 v[106:109], v[2:3], off offset:64
	global_load_dwordx4 v[110:113], v[2:3], off offset:96
	global_load_dwordx4 v[114:117], v[2:3], off offset:128
	global_load_dwordx4 v[118:121], v[2:3], off offset:160
	global_load_dwordx4 v[122:125], v[2:3], off offset:192
	global_load_dwordx4 v[126:129], v[2:3], off offset:224
	v_lshrrev_b32_e32 v3, 1, v138
	v_lshlrev_b32_e32 v4, 2, v141
	s_add_u32 s4, s24, s35
	v_lshlrev_b32_e32 v18, 3, v139
	v_bfe_u32 v10, v138, 2, 2
	v_and_b32_e32 v12, 8, v3
	v_and_b32_e32 v14, -16, v4
	v_lshlrev_b32_e32 v4, 1, v141
	s_addc_u32 s5, s25, 0
	v_and_b32_e32 v11, 24, v18
	v_and_b32_e32 v13, 0x60, v138
	v_or_b32_e32 v6, v12, v10
	v_and_b32_e32 v15, 4, v4
	s_add_u32 s4, s4, s52
	v_or_b32_e32 v2, v11, v13
	v_or3_b32 v4, v6, v15, v14
	s_addc_u32 s5, s5, s53
	v_lshlrev_b32_e32 v2, 1, v2
	v_mov_b32_e32 v3, v1
	v_ashrrev_i32_e32 v5, 31, v4
	v_lshl_add_u64 v[2:3], s[4:5], 0, v[2:3]
	v_lshlrev_b64 v[4:5], 11, v[4:5]
	v_lshl_add_u64 v[4:5], v[2:3], 0, v[4:5]
	v_add_u32_e32 v17, 32, v14
	v_lshl_add_u64 v[20:21], v[4:5], 0, s[60:61]
	v_or3_b32 v4, v17, v15, v6
	v_ashrrev_i32_e32 v5, 31, v4
	v_lshlrev_b64 v[4:5], 11, v[4:5]
	v_lshl_add_u64 v[2:3], v[2:3], 0, v[4:5]
	v_lshlrev_b32_e32 v16, 4, v139
	v_lshl_add_u64 v[22:23], v[2:3], 0, s[60:61]
	v_lshlrev_b32_e32 v2, 10, v141
	v_or_b32_e32 v8, v2, v16
	v_bfe_i32 v2, v141, 21, 1
	v_add_u32_sdwa v3, v8, v2 dst_sel:DWORD dst_unused:UNUSED_PAD src0_sel:DWORD src1_sel:BYTE_3
	v_ashrrev_i32_e32 v2, 8, v3
	v_and_b32_e32 v4, 7, v2
	v_lshrrev_b32_e32 v5, 1, v2
	v_and_b32_e32 v3, 0xffffff00, v3
	v_and_or_b32 v4, v5, 8, v4
	v_sub_u32_e32 v3, v8, v3
	v_lshlrev_b32_e32 v4, 4, v4
	v_xor_b32_e32 v4, v4, v3
	v_ashrrev_i32_e32 v3, 31, v2
	v_lshlrev_b64 v[2:3], 11, v[2:3]
	v_ashrrev_i32_e32 v4, 1, v4
	v_lshl_add_u64 v[6:7], s[4:5], 0, v[2:3]
	v_ashrrev_i32_e32 v5, 31, v4
	v_lshl_add_u64 v[24:25], v[4:5], 1, v[6:7]
	v_add_u32_e32 v7, 0x2000, v8
	v_ashrrev_i32_e32 v6, 31, v7
	v_add_u32_sdwa v8, v7, v6 dst_sel:DWORD dst_unused:UNUSED_PAD src0_sel:DWORD src1_sel:BYTE_3
	v_ashrrev_i32_e32 v6, 8, v8
	v_and_b32_e32 v8, 0xffffff00, v8
	v_sub_u32_e32 v7, v7, v8
	v_and_b32_e32 v8, 7, v6
	v_lshrrev_b32_e32 v9, 1, v6
	v_and_or_b32 v8, v9, 8, v8
	v_lshlrev_b32_e32 v8, 4, v8
	v_xor_b32_e32 v8, v8, v7
	v_ashrrev_i32_e32 v7, 31, v6
	v_lshlrev_b64 v[6:7], 11, v[6:7]
	v_lshl_add_u64 v[26:27], s[4:5], 0, v[6:7]
	v_readfirstlane_b32 s4, v141
	s_lshl_b32 s4, s4, 10
	s_add_i32 s17, s4, 0
	s_mov_b32 m0, s17
	v_ashrrev_i32_e32 v8, 1, v8
	s_add_i32 s4, s17, 0x8000
	global_load_lds_dwordx4 v[20:21], off
	s_add_i32 m0, s17, 0x2000
	v_ashrrev_i32_e32 v9, 31, v8
	global_load_lds_dwordx4 v[22:23], off
	s_mov_b32 m0, s4
	v_lshl_add_u64 v[26:27], v[8:9], 1, v[26:27]
	global_load_lds_dwordx4 v[24:25], off
	s_add_i32 m0, s17, 0xa000
	v_cmp_lt_i32_e32 vcc, 3, v141
	global_load_lds_dwordx4 v[26:27], off
	s_waitcnt vmcnt(0)
	s_waitcnt vmcnt(0) lgkmcnt(0)
	s_barrier
	s_and_saveexec_b64 s[4:5], vcc
	s_cbranch_execz .Lprio_skip_4
	s_setprio 1
; template <int DQK, int MODE>
; DI void attn_body(const AttnArgs& a, char* lds) {
;     ...
;     constexpr int NI = 2 + KCH;
;     const bf16_t* sp[NI]; int sld[NI];
; #pragma unroll
;     for (int i = 0; i < NI; ++i) { const int b = wid + 8 * i;
;         if (i < 2) { const int pos = b * 1024 + lane * 16, stl = pos >> 9, q = (pos & 511) >> 1, kk = (stl >> 2) * 8 + (q >> 5), c = (stl & 3) * 32 + (q & 31);
;             const int k = (kk & ~0xC) | ((kk & 4) << 1) | ((kk & 8) >> 1);
;             sp[i] = a.V + (size_t)k * a.ldv + c; sld[i] = a.ldv;
;         } else { const int pos = (b - 16) * 1024 + lane * 16, row = pos / KROWB, within = pos - row * KROWB, c = (within ^ ksw(row)) >> 4;
;             if (MODE == 2 && c >= 16) { sp[i] = a.K2 + (size_t)row * a.ldk2 + (c - 16) * 8; sld[i] = a.ldk2; }
;             else { sp[i] = a.K + (size_t)row * a.ldk + c * 8; sld[i] = a.ldk; } } }
;     const int wu = __builtin_amdgcn_readfirstlane(wid);
;     ...
;     constexpr int NB = (KROWB == 256) ? 8 : 4;
;     int kb[NB];
;     { const int X = (hi * 16) ^ ksw(r32);
; #pragma unroll
;       for (int i = 0; i < NB; ++i) kb[i] = (int)(uintptr_t)K_lds + r32 * KROWB + ((i * 32) ^ X); }
;     const int qra = (int)(uintptr_t)qrl;
.Lprio_skip_4:
	s_or_b64 exec, exec, s[4:5]
	v_and_b32_e32 v19, 0x3fffffc0, v138
	s_add_i32 s4, 0, 0x14000
	s_lshl_b32 s16, s16, 17
	v_lshl_add_u32 v144, v19, 2, s4
	s_add_i32 s4, 0, 0x8000
	s_cmp_lg_u32 s4, -1
	v_lshlrev_b32_e32 v19, 1, v139
	v_and_b32_e32 v18, 0x100, v18
	s_cselect_b32 s4, s4, 0
	v_and_b32_e32 v16, 0xc0, v16
	s_cmp_lg_u32 0, -1
	v_and_b32_e32 v19, 32, v19
	v_or3_b32 v16, v16, v18, v11
	s_cselect_b32 s36, 0, 0
	v_add3_u32 v154, v19, s36, v16
	v_add_u32_e32 v16, v17, v12
	v_add3_u32 v16, v16, v15, v10
	v_add_lshl_u32 v18, v13, v11, 1
	v_add_u32_e32 v11, v14, v12
	v_ashrrev_i32_e32 v17, 31, v16
	s_add_u32 s36, s52, s35
	v_add3_u32 v10, v11, v15, v10
	v_lshlrev_b64 v[16:17], 11, v[16:17]
	s_addc_u32 s37, s53, 0
	v_ashrrev_i32_e32 v11, 31, v10
	v_and_b32_e32 v20, 7, v138
	v_lshl_add_u64 v[16:17], s[36:37], 0, v[16:17]
	v_mov_b32_e32 v19, v1
	v_lshlrev_b64 v[10:11], 11, v[10:11]
	v_bitop3_b32 v20, v12, v142, v20 bitop3:0x36
	v_lshl_add_u64 v[16:17], v[16:17], 0, v[18:19]
	v_lshl_add_u64 v[10:11], s[36:37], 0, v[10:11]
	v_lshl_add_u64 v[6:7], s[36:37], 0, v[6:7]
	v_lshl_add_u64 v[2:3], s[36:37], 0, v[2:3]
	v_lshlrev_b32_e32 v20, 4, v20
	v_lshl_add_u32 v21, v143, 8, s4
	v_lshl_add_u64 v[130:131], s[10:11], 0, v[16:17]
	v_lshl_add_u64 v[10:11], v[10:11], 0, v[18:19]
	v_lshl_add_u64 v[6:7], v[8:9], 1, v[6:7]
	v_lshl_add_u64 v[2:3], v[4:5], 1, v[2:3]
	v_mov_b32_e32 v16, v1
	v_mov_b32_e32 v17, v1
	v_add_u32_e32 v145, v20, v21
	v_xad_u32 v146, v20, 32, v21
	v_xad_u32 v148, v20, 64, v21
	v_xad_u32 v149, v20, s13, v21
	v_xad_u32 v150, v20, s31, v21
	v_xad_u32 v151, v20, s83, v21
	v_xad_u32 v152, v20, s73, v21
	v_xad_u32 v153, v20, s58, v21
	v_lshl_add_u64 v[132:133], s[10:11], 0, v[10:11]
	v_lshl_add_u64 v[134:135], s[50:51], 0, v[6:7]
	v_lshl_add_u64 v[136:137], s[50:51], 0, v[2:3]
	v_mov_b32_e32 v2, v1
	v_mov_b32_e32 v3, v1
	v_mov_b32_e32 v4, v1
	v_mov_b32_e32 v5, v1
	v_mov_b32_e32 v6, v1
	v_mov_b32_e32 v7, v1
	v_mov_b32_e32 v8, v1
	v_mov_b32_e32 v9, v1
	v_mov_b32_e32 v10, v1
	v_mov_b32_e32 v11, v1
	v_mov_b32_e32 v12, v1
	v_mov_b32_e32 v13, v1
	v_mov_b32_e32 v14, v1
	v_mov_b32_e32 v15, v1
	v_mov_b64_e32 v[64:65], v[16:17]
	v_mov_b64_e32 v[48:49], v[16:17]
	v_mov_b64_e32 v[32:33], v[16:17]
	s_mov_b32 s33, 0
	v_cmp_gt_u32_e64 s[4:5], 32, v139
	v_lshl_add_u32 v147, v143, 2, v144
	v_mov_b32_e32 v155, 0xf149f2ca
	v_mov_b32_e32 v156, 0
	s_mov_b64 s[54:55], 0
	v_mov_b64_e32 v[62:63], v[14:15]
	v_mov_b64_e32 v[60:61], v[12:13]
	v_mov_b64_e32 v[58:59], v[10:11]
	v_mov_b64_e32 v[56:57], v[8:9]
	v_mov_b64_e32 v[54:55], v[6:7]
	v_mov_b64_e32 v[52:53], v[4:5]
	v_mov_b64_e32 v[50:51], v[2:3]
	v_mov_b64_e32 v[46:47], v[14:15]
	v_mov_b64_e32 v[44:45], v[12:13]
	v_mov_b64_e32 v[42:43], v[10:11]
	v_mov_b64_e32 v[40:41], v[8:9]
	v_mov_b64_e32 v[38:39], v[6:7]
	v_mov_b64_e32 v[36:37], v[4:5]
	v_mov_b64_e32 v[34:35], v[2:3]
	v_mov_b64_e32 v[30:31], v[14:15]
	v_mov_b64_e32 v[28:29], v[12:13]
	v_mov_b64_e32 v[26:27], v[10:11]
	v_mov_b64_e32 v[24:25], v[8:9]
	v_mov_b64_e32 v[22:23], v[6:7]
	v_mov_b64_e32 v[20:21], v[4:5]
	v_mov_b64_e32 v[18:19], v[2:3]
	s_and_b32 s36, s33, 1
	s_cmp_lt_u32 s33, 3
	s_mov_b64 s[56:57], -1
	s_cbranch_scc1 .LBB0_825
